# P2->P3 without grid barrier: write-through MIX/Y-slice stores, completion counters (all items / PA+conv), workgroups start out-proj when PA+conv done; sample slice recomputed after unit
# baseline (speedup 1.0000x reference)
_Z8mega_fwd6Params:
	s_mov_b32 s101, 0
	v_writelane_b32 v251, s0, 0
	v_writelane_b32 v251, s1, 1
	s_load_dwordx4 s[16:19], s[0:1], 0x80
	s_mov_b32 s50, s2
	s_mov_b64 s[52:53], s[0:1]
	v_cmp_gt_u32_e32 vcc, 64, v0
	s_and_saveexec_b64 s[0:1], vcc
	v_lshl_add_u32 v1, v0, 2, 0
	v_add_u32_e32 v1, 0x23200, v1
	v_mov_b32_e32 v2, 0
	ds_write_b32 v1, v2
	s_or_b64 exec, exec, s[0:1]
	s_load_dwordx16 s[0:15], s[52:53], 0x0
	s_waitcnt lgkmcnt(0)
	s_barrier
	v_cmp_eq_u32_e64 s[48:49], 0, v0
	v_writelane_b32 v248, s0, 0
	s_nop 1
	v_writelane_b32 v248, s1, 1
	v_writelane_b32 v248, s2, 2
	v_writelane_b32 v248, s3, 3
	v_writelane_b32 v248, s4, 4
	v_writelane_b32 v248, s5, 5
	v_writelane_b32 v248, s6, 6
	v_writelane_b32 v248, s7, 7
	v_writelane_b32 v248, s8, 8
	v_writelane_b32 v248, s9, 9
	v_writelane_b32 v248, s10, 10
	v_writelane_b32 v248, s11, 11
	v_writelane_b32 v248, s12, 12
	v_writelane_b32 v248, s13, 13
	v_writelane_b32 v248, s14, 14
	v_writelane_b32 v248, s15, 15
	s_load_dwordx16 s[0:15], s[52:53], 0x40
	s_waitcnt lgkmcnt(0)
	v_writelane_b32 v248, s0, 16
	s_nop 1
	v_writelane_b32 v248, s1, 17
	v_writelane_b32 v248, s2, 18
	v_writelane_b32 v248, s3, 19
	v_writelane_b32 v248, s4, 20
	v_writelane_b32 v248, s5, 21
	v_writelane_b32 v248, s6, 22
	v_writelane_b32 v248, s7, 23
	v_writelane_b32 v248, s8, 24
	v_writelane_b32 v248, s9, 25
	v_writelane_b32 v248, s10, 26
	v_writelane_b32 v248, s11, 27
	v_writelane_b32 v248, s12, 28
	v_writelane_b32 v248, s13, 29
	v_writelane_b32 v248, s14, 30
	v_writelane_b32 v248, s15, 31
	s_add_u32 s0, s16, 0x1000
	v_writelane_b32 v248, s16, 32
	s_addc_u32 s1, s17, 0
	s_nop 0
	v_writelane_b32 v248, s17, 33
	v_writelane_b32 v248, s18, 34
	v_writelane_b32 v248, s19, 35
	v_writelane_b32 v248, s0, 36
	s_nop 1
	v_writelane_b32 v248, s1, 37
	s_getreg_b32 s0, hwreg(HW_REG_XCC_ID, 0, 4)
	s_and_b32 s33, s0, 15
	s_and_saveexec_b64 s[0:1], s[48:49]
	s_cbranch_execz .LBB0_5
	s_mov_b64 s[2:3], exec
	v_mbcnt_lo_u32_b32 v1, s2, 0
	v_mbcnt_hi_u32_b32 v1, s3, v1
	v_cmp_eq_u32_e32 vcc, 0, v1
	s_and_b64 s[4:5], exec, vcc
	s_mov_b64 exec, s[4:5]
	s_cbranch_execz .LBB0_5
	s_bcnt1_i32_b64 s2, s[2:3]
	s_lshl_b32 s4, s33, 8
	v_mov_b32_e32 v2, s2
	v_readlane_b32 s2, v248, 36
	v_mov_b32_e32 v1, s4
	v_readlane_b32 s3, v248, 37
	s_nop 4
	global_atomic_add v1, v2, s[2:3] offset:1024

.LBB0_436:
	s_mov_b32 s32, 0
	s_load_dwordx4 s[28:31], s[52:53], 0x80
	s_waitcnt lgkmcnt(0)
	s_cmp_lt_i32 s30, 3
	s_cselect_b64 s[0:1], -1, 0
	s_and_b64 s[0:1], s[0:1], s[6:7]
	s_andn2_b64 vcc, exec, s[0:1]
	s_cbranch_vccnz .LBB0_610
	s_load_dwordx16 s[12:27], s[52:53], 0x0
	v_writelane_b32 v248, s0, 48
	v_mbcnt_lo_u32_b32 v3, -1, 0
	s_mov_b32 s11, 0x27000
	v_writelane_b32 v248, s1, 49
	s_waitcnt lgkmcnt(0)
	s_mov_b64 s[6:7], s[18:19]
	s_and_b32 s9, s7, 0xffff
	v_writelane_b32 v248, s33, 46
	s_add_u32 s0, s28, 0x2900000
	v_writelane_b32 v248, s0, 47
	s_addc_u32 s0, s29, 0
	v_writelane_b32 v248, s0, 44
	s_add_i32 s2, 0, 0x23200
	s_brev_b32 s10, -2
	s_mov_b32 s8, s18
	s_mov_b64 s[0:1], -1
	s_mov_b32 s21, 0
	v_mov_b32_e32 v2, 0
	v_writelane_b32 v248, s2, 38
	v_mov_b32_e32 v1, s2
	s_add_i32 s51, 0, 0x20000
	s_movk_i32 s33, 0x1000
	s_movk_i32 s50, 0x2000
	s_add_i32 s2, 0, 0x20800
	s_movk_i32 s19, 0x3000
	s_add_i32 s46, 0, 0x10000
	s_movk_i32 s6, 0x4000
	s_movk_i32 s17, 0x6000
	s_mov_b32 s31, 0x41000000
	s_movk_i32 s22, 0x5000
	s_movk_i32 s30, 0x7000
	v_mov_b32_e32 v204, 0x358637bd
	s_mov_b32 s18, 0xf800000
	v_mov_b32_e32 v205, 0x260
	v_mov_b32_e32 v196, 0xe0ad78ec
	v_mbcnt_hi_u32_b32 v206, -1, v3
	v_mov_b32_e32 v207, 3
	v_mov_b32_e32 v208, 2
	v_mov_b32_e32 v209, 1
	s_mov_b64 s[26:27], 0x100
	s_mov_b64 s[28:29], 0x1800
	s_mov_b64 s[34:35], 0x1900
	v_writelane_b32 v248, s2, 50
	s_branch .LBB0_440

.LBB0_440:
	s_waitcnt vmcnt(0)
	s_mov_b64 s[2:3], exec
	v_readlane_b32 s4, v248, 40
	v_readlane_b32 s5, v248, 41
	s_and_b64 s[4:5], s[2:3], s[4:5]
	s_mov_b64 exec, s[4:5]
	s_cbranch_execz .LBB0_448
	s_load_dwordx4 s[4:7], s[52:53], 0x80
	v_mov_b32_e32 v4, 1
	s_waitcnt lgkmcnt(0)
	global_atomic_add v4, v2, v4, s[4:5] offset:256 sc0
	s_waitcnt vmcnt(0)
	v_readfirstlane_b32 s0, v4
	s_movk_i32 s6, 0x4000
	s_nop 0
	v_mov_b32_e32 v3, s0
	v_readlane_b32 s0, v248, 38
	s_nop 1
	v_mov_b32_e32 v4, s0
	ds_write_b32 v4, v3
.LBB0_448:
	s_or_b64 exec, exec, s[2:3]
	s_waitcnt lgkmcnt(0)
	s_barrier
	s_cmp_eq_u32 s32, 0
	s_cbranch_scc1 .Lcmp_skip
	s_mov_b64 s[2:3], exec
	v_readlane_b32 s4, v248, 40
	v_readlane_b32 s5, v248, 41
	s_and_b64 s[4:5], s[2:3], s[4:5]
	s_mov_b64 exec, s[4:5]
	s_cbranch_execz .Lcmp_done
	s_load_dwordx2 s[4:5], s[52:53], 0x80
	v_mov_b32_e32 v3, 1
	s_waitcnt lgkmcnt(0)
	global_atomic_add v2, v3, s[4:5] offset:512
	s_cmp_lg_u32 s32, 1
	s_cbranch_scc1 .Lcmp_done
	global_atomic_add v2, v3, s[4:5] offset:1536

.Lcmp_skip:
	ds_read_b32 v3, v1
	s_mov_b64 s[2:3], -1
	s_waitcnt lgkmcnt(0)
	s_barrier
	v_readfirstlane_b32 s4, v3
	s_cmpk_gt_i32 s4, 0x381
	s_cbranch_scc1 .LBB0_439
	s_mov_b32 s32, 1
	s_cmpk_gt_i32 s4, 0x81
	s_mov_b64 s[0:1], -1
	s_cbranch_scc0 .LBB0_519
	s_cmpk_gt_u32 s4, 0x141
	s_cbranch_scc0 .LBB0_481
	s_cmpk_gt_u32 s4, 0x2f1
	s_cbranch_scc0 .LBB0_453
	s_add_i32 s5, s4, 0xfffffdfe
	s_mov_b64 s[0:1], 0

.LBB0_457:
	s_mov_b32 s32, 2
	s_sext_i32_i16 s0, s2
	s_mulk_i32 s0, 0x2aab
	s_lshr_b32 s1, s0, 31
	s_ashr_i32 s20, s0, 17
	s_load_dwordx4 s[12:15], s[52:53], 0x80
	s_add_i32 s20, s20, s1
	s_mul_i32 s0, s20, 12
	s_sub_i32 s0, s2, s0
	s_sext_i32_i16 s16, s0
	v_mov_b32_e32 v100, v0
	s_mov_b64 s[0:1], 0
	s_waitcnt lgkmcnt(0)
	s_add_u32 s6, s12, s0
	s_movk_i32 s2, 0xa80
	s_addc_u32 s7, s13, s1
	v_cmp_gt_i32_e32 vcc, s2, v100
	s_and_saveexec_b64 s[12:13], vcc
	s_cbranch_execz .LBB0_470
	v_max_i32_e32 v3, 0x880, v100
	v_sub_u32_e32 v3, v3, v100
	s_mul_i32 s14, s16, 0xa80
	v_add_u32_e32 v3, 0x1ff, v3
	s_movk_i32 s2, 0x1ff
	s_ashr_i32 s15, s14, 31
	v_cmp_lt_u32_e32 vcc, s2, v3
	s_mov_b64 s[2:3], -1
	v_mov_b32_e32 v4, v100
	s_and_saveexec_b64 s[66:67], vcc
	s_cbranch_execz .LBB0_467
	s_lshl_b64 s[2:3], s[14:15], 2
	v_lshrrev_b32_e32 v3, 9, v3
	s_add_u32 s2, s6, s2
	s_addc_u32 s3, s7, s3
	v_add_u32_e32 v4, -1, v3
	s_add_u32 s68, s2, 0x2900000
	v_add_u32_e32 v101, 0x200, v100
	v_lshrrev_b32_e32 v5, 1, v4
	s_addc_u32 s69, s3, 0
	v_add_u32_e32 v6, 1, v5
	v_cmp_lt_u32_e32 vcc, 13, v4
	v_mov_b32_e32 v9, 0
	v_mov_b64_e32 v[4:5], v[100:101]
	s_and_saveexec_b64 s[24:25], vcc
	s_cbranch_execz .LBB0_463
	v_and_b32_e32 v7, -8, v6
	v_lshl_add_u32 v8, v100, 2, s51
	s_mov_b32 s2, 0
	s_mov_b64 s[70:71], 0
	v_mov_b64_e32 v[4:5], v[100:101]

.LBB0_515:
	s_waitcnt vmcnt(0)
	s_add_i32 s15, s15, 0x10000
	s_cmp_eq_u32 s24, s3
	v_add_u32_e32 v226, 0xfffffe00, v226
	s_waitcnt vmcnt(0) lgkmcnt(0)
	s_barrier
	s_cbranch_scc0 .LBB0_498
	s_and_saveexec_b64 s[0:1], s[6:7]
	ds_write_b32 v222, v147 offset:128
	s_or_b64 exec, exec, s[0:1]
	s_waitcnt lgkmcnt(0)
	v_lshl_add_u32 v3, v211, 4, s2
	ds_read_b32 v4, v3 offset:128
	s_lshl_b32 s0, s66, 14
	v_lshlrev_b32_e32 v5, 2, v212
	v_lshlrev_b32_e32 v6, 11, v211
	s_add_i32 s0, s0, 0
	s_waitcnt lgkmcnt(0)
	v_rcp_f32_e32 v4, v4
	v_add3_u32 v6, s0, v5, v6
	v_add_u32_e32 v14, 0x3000, v6
	v_or_b32_e32 v48, 64, v213
	v_mul_f32_e32 v5, v130, v4
	v_mul_f32_e32 v7, v114, v4
	ds_write2_b32 v6, v5, v7 offset1:32
	v_mul_f32_e32 v5, v98, v4
	v_mul_f32_e32 v4, v82, v4
	ds_write2_b32 v6, v5, v4 offset0:64 offset1:96
	ds_read_b32 v4, v3 offset:132
	v_or_b32_e32 v49, 0x80, v213
	s_lshl_b32 s20, s20, 1
	v_and_b32_e32 v38, 0x78, v210
	v_mov_b32_e32 v13, v2
	s_waitcnt lgkmcnt(0)
	v_rcp_f32_e32 v4, v4
	v_or_b32_e32 v50, 0x100, v213
	v_or_b32_e32 v51, 0x140, v213
	v_or_b32_e32 v52, 0x180, v213
	v_mul_f32_e32 v5, v131, v4
	v_mul_f32_e32 v7, v115, v4
	v_mul_f32_e32 v8, v99, v4
	v_mul_f32_e32 v4, v83, v4
	ds_write2_b32 v6, v5, v7 offset0:128 offset1:160
	ds_write2_b32 v6, v8, v4 offset0:192 offset1:224
	ds_read_b32 v4, v3 offset:136
	v_add_u32_e32 v5, 0x400, v6
	v_or_b32_e32 v53, 0x1c0, v213
	s_waitcnt lgkmcnt(0)
	v_rcp_f32_e32 v4, v4
	s_nop 0
	v_mul_f32_e32 v7, v132, v4
	v_mul_f32_e32 v8, v116, v4
	v_mul_f32_e32 v9, v100, v4
	v_mul_f32_e32 v4, v84, v4
	ds_write2_b32 v5, v7, v8 offset1:32
	ds_write2_b32 v5, v9, v4 offset0:64 offset1:96
	ds_read_b32 v4, v3 offset:140
	s_waitcnt lgkmcnt(0)
	v_rcp_f32_e32 v4, v4
	s_nop 0
	v_mul_f32_e32 v7, v133, v4
	v_mul_f32_e32 v8, v117, v4
	v_mul_f32_e32 v9, v101, v4
	v_mul_f32_e32 v4, v85, v4
	ds_write2_b32 v5, v7, v8 offset0:128 offset1:160
	ds_write2_b32 v5, v9, v4 offset0:192 offset1:224
	ds_read_b32 v4, v3 offset:160
	v_add_u32_e32 v5, 0x1000, v6
	s_waitcnt lgkmcnt(0)
	v_rcp_f32_e32 v4, v4
	s_nop 0
	v_mul_f32_e32 v7, v134, v4
	v_mul_f32_e32 v8, v118, v4
	v_mul_f32_e32 v9, v102, v4
	v_mul_f32_e32 v4, v86, v4
	ds_write2_b32 v5, v7, v8 offset1:32
	ds_write2_b32 v5, v9, v4 offset0:64 offset1:96
	ds_read_b32 v4, v3 offset:164
	s_waitcnt lgkmcnt(0)
	v_rcp_f32_e32 v4, v4
	s_nop 0
	v_mul_f32_e32 v7, v135, v4
	v_mul_f32_e32 v8, v119, v4
	v_mul_f32_e32 v9, v103, v4
	v_mul_f32_e32 v4, v87, v4
	ds_write2_b32 v5, v7, v8 offset0:128 offset1:160
	ds_write2_b32 v5, v9, v4 offset0:192 offset1:224
	ds_read_b32 v4, v3 offset:168
	v_add_u32_e32 v5, 0x1400, v6
	s_waitcnt lgkmcnt(0)
	v_rcp_f32_e32 v4, v4
	s_nop 0
	v_mul_f32_e32 v7, v136, v4
	v_mul_f32_e32 v8, v120, v4
	v_mul_f32_e32 v9, v104, v4
	v_mul_f32_e32 v4, v88, v4
	ds_write2_b32 v5, v7, v8 offset1:32
	ds_write2_b32 v5, v9, v4 offset0:64 offset1:96
	ds_read_b32 v4, v3 offset:172
	s_waitcnt lgkmcnt(0)
	v_rcp_f32_e32 v4, v4
	s_nop 0
	v_mul_f32_e32 v7, v137, v4
	v_mul_f32_e32 v8, v121, v4
	v_mul_f32_e32 v9, v105, v4
	v_mul_f32_e32 v4, v89, v4
	ds_write2_b32 v5, v7, v8 offset0:128 offset1:160
	ds_write2_b32 v5, v9, v4 offset0:192 offset1:224
	ds_read_b32 v4, v3 offset:192
	v_add_u32_e32 v5, 0x2000, v6
	s_waitcnt lgkmcnt(0)
	v_rcp_f32_e32 v4, v4
	s_nop 0
	v_mul_f32_e32 v7, v138, v4
	v_mul_f32_e32 v8, v122, v4
	v_mul_f32_e32 v9, v106, v4
	v_mul_f32_e32 v4, v90, v4
	ds_write2_b32 v5, v7, v8 offset1:32
	ds_write2_b32 v5, v9, v4 offset0:64 offset1:96
	ds_read_b32 v4, v3 offset:196
	s_waitcnt lgkmcnt(0)
	v_rcp_f32_e32 v4, v4
	s_nop 0
	v_mul_f32_e32 v7, v139, v4
	v_mul_f32_e32 v8, v123, v4
	v_mul_f32_e32 v9, v107, v4
	v_mul_f32_e32 v4, v91, v4
	ds_write2_b32 v5, v7, v8 offset0:128 offset1:160
	ds_write2_b32 v5, v9, v4 offset0:192 offset1:224
	ds_read_b32 v4, v3 offset:200
	v_add_u32_e32 v7, 0x2400, v6
	s_waitcnt lgkmcnt(0)
	v_rcp_f32_e32 v4, v4
	s_nop 0
	v_mul_f32_e32 v5, v140, v4
	v_mul_f32_e32 v8, v124, v4
	v_mul_f32_e32 v9, v108, v4
	v_mul_f32_e32 v4, v92, v4
	ds_write2_b32 v7, v5, v8 offset1:32
	ds_write2_b32 v7, v9, v4 offset0:64 offset1:96
	ds_read_b32 v4, v3 offset:204
	v_and_or_b32 v8, v199, 24, s5
	v_add_u32_e32 v8, s66, v8
	s_waitcnt lgkmcnt(0)
	v_rcp_f32_e32 v9, v4
	v_mov_b64_e32 v[4:5], s[68:69]
	v_mul_f32_e32 v10, v141, v9
	v_mul_f32_e32 v11, v125, v9
	v_mul_f32_e32 v12, v109, v9
	v_mul_f32_e32 v9, v93, v9
	ds_write2_b32 v7, v10, v11 offset0:128 offset1:160
	ds_write2_b32 v7, v12, v9 offset0:192 offset1:224
	ds_read_b32 v7, v3 offset:224
	v_lshrrev_b32_e32 v10, 1, v48
	v_lshrrev_b32_e32 v11, 1, v49
	v_and_or_b32 v10, v10, 56, s5
	v_and_b32_e32 v11, 0x58, v11
	s_waitcnt lgkmcnt(0)
	v_rcp_f32_e32 v7, v7
	v_lshlrev_b32_e32 v12, 1, v38
	v_mul_f32_e32 v9, v142, v7
	v_mul_f32_e32 v15, v126, v7
	v_mul_f32_e32 v16, v110, v7
	v_mul_f32_e32 v7, v94, v7
	ds_write2_b32 v14, v9, v15 offset1:32
	ds_write2_b32 v14, v16, v7 offset0:64 offset1:96
	ds_read_b32 v7, v3 offset:228
	v_mad_i64_i32 v[8:9], s[2:3], v8, s19, v[4:5]
	v_add_u32_e32 v15, 0x3400, v6
	s_waitcnt lgkmcnt(0)
	v_rcp_f32_e32 v16, v7
	v_lshl_add_u64 v[6:7], v[8:9], 0, s[20:21]
	v_add_u32_e32 v8, s66, v10
	v_or_b32_e32 v10, s5, v11
	v_mul_f32_e32 v9, v143, v16
	v_mul_f32_e32 v11, v127, v16
	v_mul_f32_e32 v17, v111, v16
	v_mul_f32_e32 v16, v95, v16
	ds_write2_b32 v14, v9, v11 offset0:128 offset1:160
	ds_write2_b32 v14, v17, v16 offset0:192 offset1:224
	ds_read_b32 v11, v3 offset:232
	v_lshl_add_u64 v[6:7], v[6:7], 0, v[12:13]
	v_mad_i64_i32 v[8:9], s[2:3], v8, s19, v[4:5]
	v_add_co_u32_e32 v6, vcc, s50, v6
	s_waitcnt lgkmcnt(0)
	v_rcp_f32_e32 v11, v11
	v_lshl_add_u64 v[8:9], v[8:9], 0, s[20:21]
	v_addc_co_u32_e32 v7, vcc, 0, v7, vcc
	v_mul_f32_e32 v14, v144, v11
	v_mul_f32_e32 v16, v128, v11
	v_mul_f32_e32 v17, v112, v11
	v_mul_f32_e32 v11, v96, v11
	ds_write2_b32 v15, v14, v16 offset1:32
	ds_write2_b32 v15, v17, v11 offset0:64 offset1:96
	ds_read_b32 v3, v3 offset:236
	v_lshl_add_u64 v[8:9], v[8:9], 0, v[12:13]
	v_add_co_u32_e32 v8, vcc, s50, v8
	v_add_u32_e32 v10, s66, v10
	s_waitcnt lgkmcnt(0)
	v_rcp_f32_e32 v3, v3
	v_addc_co_u32_e32 v9, vcc, 0, v9, vcc
	v_mad_i64_i32 v[10:11], s[2:3], v10, s19, v[4:5]
	v_mul_f32_e32 v14, v145, v3
	v_mul_f32_e32 v16, v129, v3
	v_mul_f32_e32 v17, v113, v3
	v_mul_f32_e32 v3, v97, v3
	ds_write2_b32 v15, v14, v16 offset0:128 offset1:160
	ds_write2_b32 v15, v17, v3 offset0:192 offset1:224
	s_waitcnt lgkmcnt(0)
	v_or_b32_e32 v3, 0xc0, v213
	global_load_dwordx4 v[14:17], v[6:7], off offset:1024
	global_load_dwordx4 v[18:21], v[8:9], off offset:1024
	v_lshrrev_b32_e32 v8, 1, v3
	v_and_b32_e32 v8, 0x78, v8
	v_or_b32_e32 v8, s5, v8
	v_lshl_add_u64 v[6:7], v[10:11], 0, s[20:21]
	v_add_u32_e32 v8, s66, v8
	v_lshl_add_u64 v[6:7], v[6:7], 0, v[12:13]
	v_mad_i64_i32 v[8:9], s[2:3], v8, s19, v[4:5]
	v_add_co_u32_e32 v6, vcc, s50, v6
	v_lshl_add_u64 v[8:9], v[8:9], 0, s[20:21]
	s_nop 0
	v_addc_co_u32_e32 v7, vcc, 0, v7, vcc
	v_lshl_add_u64 v[8:9], v[8:9], 0, v[12:13]
	v_add_co_u32_e32 v8, vcc, s50, v8
	s_nop 1
	v_addc_co_u32_e32 v9, vcc, 0, v9, vcc
	global_load_dwordx4 v[22:25], v[6:7], off offset:1024
	global_load_dwordx4 v[26:29], v[8:9], off offset:1024
	v_lshrrev_b32_e32 v6, 1, v50
	v_and_b32_e32 v6, 0x98, v6
	v_or_b32_e32 v6, s5, v6
	v_lshrrev_b32_e32 v8, 1, v51
	v_add_u32_e32 v6, s66, v6
	v_and_b32_e32 v8, 0xb8, v8
	v_mad_i64_i32 v[6:7], s[2:3], v6, s19, v[4:5]
	v_or_b32_e32 v8, s5, v8
	v_lshl_add_u64 v[6:7], v[6:7], 0, s[20:21]
	v_add_u32_e32 v8, s66, v8
	v_lshl_add_u64 v[6:7], v[6:7], 0, v[12:13]
	v_mad_i64_i32 v[8:9], s[2:3], v8, s19, v[4:5]
	v_add_co_u32_e32 v6, vcc, s50, v6
	v_lshl_add_u64 v[8:9], v[8:9], 0, s[20:21]
	s_nop 0
	v_addc_co_u32_e32 v7, vcc, 0, v7, vcc
	v_lshl_add_u64 v[8:9], v[8:9], 0, v[12:13]
	v_add_co_u32_e32 v8, vcc, s50, v8
	s_nop 1
	v_addc_co_u32_e32 v9, vcc, 0, v9, vcc
	global_load_dwordx4 v[30:33], v[6:7], off offset:1024
	global_load_dwordx4 v[34:37], v[8:9], off offset:1024
	v_lshrrev_b32_e32 v6, 1, v52
	v_and_b32_e32 v6, 0xd8, v6
	v_or_b32_e32 v6, s5, v6
	v_lshrrev_b32_e32 v8, 1, v53
	v_add_u32_e32 v6, s66, v6
	v_and_b32_e32 v8, 0xf8, v8
	v_mad_i64_i32 v[6:7], s[2:3], v6, s19, v[4:5]
	v_or_b32_e32 v8, s5, v8
	v_lshl_add_u64 v[6:7], v[6:7], 0, s[20:21]
	v_add_u32_e32 v8, s66, v8
	v_lshl_add_u64 v[6:7], v[6:7], 0, v[12:13]
	v_mad_i64_i32 v[4:5], s[2:3], v8, s19, v[4:5]
	v_add_co_u32_e32 v6, vcc, s50, v6
	v_lshl_add_u64 v[4:5], v[4:5], 0, s[20:21]
	s_nop 0
	v_addc_co_u32_e32 v7, vcc, 0, v7, vcc
	v_lshl_add_u64 v[4:5], v[4:5], 0, v[12:13]
	v_add_co_u32_e32 v4, vcc, s50, v4
	s_nop 1
	v_addc_co_u32_e32 v5, vcc, 0, v5, vcc
	global_load_dwordx4 v[8:11], v[6:7], off offset:1024
	s_nop 0
	global_load_dwordx4 v[4:7], v[4:5], off offset:1024
	v_lshl_add_u32 v54, v38, 2, s0
	v_lshl_add_u32 v44, v197, 9, v54
	ds_read_b128 v[38:41], v44
	v_lshl_or_b32 v42, v197, 3, s5
	v_mov_b32_e32 v43, v2
	v_lshl_add_u64 v[46:47], v[42:43], 0, s[66:67]
	ds_read_b128 v[42:45], v44 offset:16
	s_waitcnt vmcnt(7)
	v_lshlrev_b32_e32 v55, 16, v14
	v_and_b32_e32 v14, 0xffff0000, v14
	s_waitcnt lgkmcnt(1)
	v_mul_f32_e32 v38, v38, v55
	v_mul_f32_e32 v14, v39, v14
	v_cvt_pk_bf16_f32 v14, v38, v14
	v_lshlrev_b32_e32 v38, 16, v15
	v_and_b32_e32 v15, 0xffff0000, v15
	v_mul_f32_e32 v38, v40, v38
	v_mul_f32_e32 v15, v41, v15
	v_cvt_pk_bf16_f32 v15, v38, v15
	v_lshlrev_b32_e32 v38, 16, v16
	v_and_b32_e32 v16, 0xffff0000, v16
	s_add_u32 s0, s36, s20
	s_waitcnt lgkmcnt(0)
	v_mul_f32_e32 v38, v42, v38
	v_mul_f32_e32 v16, v43, v16
	s_addc_u32 s1, s37, 0
	v_cvt_pk_bf16_f32 v16, v38, v16
	v_lshlrev_b32_e32 v38, 16, v17
	v_and_b32_e32 v17, 0xffff0000, v17
	v_lshl_add_u64 v[12:13], s[0:1], 0, v[12:13]
	s_mov_b64 s[0:1], 0xc600000
	v_mul_f32_e32 v38, v44, v38
	v_mul_f32_e32 v17, v45, v17
	v_lshl_add_u64 v[12:13], v[12:13], 0, s[0:1]
	v_cvt_pk_bf16_f32 v17, v38, v17
	v_lshlrev_b64 v[38:39], 12, v[46:47]
	v_lshl_add_u64 v[38:39], v[12:13], 0, v[38:39]
	global_store_dwordx4 v[38:39], v[14:17], off sc0 sc1
	v_mov_b32_e32 v39, v2
	s_waitcnt vmcnt(7)
	v_lshlrev_b32_e32 v44, 16, v18
	v_lshrrev_b32_e32 v14, 4, v48
	v_lshl_add_u32 v40, v14, 9, v54
	v_lshl_or_b32 v38, v14, 3, s5
	ds_read_b128 v[14:17], v40
	v_and_b32_e32 v18, 0xffff0000, v18
	v_lshl_add_u64 v[42:43], v[38:39], 0, s[66:67]
	ds_read_b128 v[38:41], v40 offset:16
	v_lshrrev_b32_e32 v3, 4, v3
	s_waitcnt lgkmcnt(1)
	v_mul_f32_e32 v14, v14, v44
	v_mul_f32_e32 v15, v15, v18
	v_cvt_pk_bf16_f32 v14, v14, v15
	v_lshlrev_b32_e32 v15, 16, v19
	v_mul_f32_e32 v15, v16, v15
	v_and_b32_e32 v16, 0xffff0000, v19
	v_mul_f32_e32 v16, v17, v16
	v_cvt_pk_bf16_f32 v15, v15, v16
	v_lshlrev_b32_e32 v16, 16, v20
	v_and_b32_e32 v17, 0xffff0000, v20
	s_waitcnt lgkmcnt(0)
	v_mul_f32_e32 v16, v38, v16
	v_mul_f32_e32 v17, v39, v17
	v_cvt_pk_bf16_f32 v16, v16, v17
	v_lshlrev_b32_e32 v17, 16, v21
	v_and_b32_e32 v18, 0xffff0000, v21
	v_mul_f32_e32 v17, v40, v17
	v_mul_f32_e32 v18, v41, v18
	v_cvt_pk_bf16_f32 v17, v17, v18
	v_lshlrev_b64 v[18:19], 12, v[42:43]
	v_lshl_add_u64 v[18:19], v[12:13], 0, v[18:19]
	global_store_dwordx4 v[18:19], v[14:17], off sc0 sc1
	v_mov_b32_e32 v19, v2
	s_waitcnt vmcnt(7)
	v_lshlrev_b32_e32 v40, 16, v22
	v_lshrrev_b32_e32 v14, 4, v49
	v_lshl_add_u32 v20, v14, 9, v54
	v_lshl_or_b32 v18, v14, 3, s5
	ds_read_b128 v[14:17], v20
	v_and_b32_e32 v22, 0xffff0000, v22
	v_lshl_add_u64 v[38:39], v[18:19], 0, s[66:67]
	ds_read_b128 v[18:21], v20 offset:16
	s_movk_i32 s6, 0x4000
	s_waitcnt lgkmcnt(1)
	v_mul_f32_e32 v14, v14, v40
	v_mul_f32_e32 v15, v15, v22
	v_cvt_pk_bf16_f32 v14, v14, v15
	v_lshlrev_b32_e32 v15, 16, v23
	v_mul_f32_e32 v15, v16, v15
	v_and_b32_e32 v16, 0xffff0000, v23
	v_mul_f32_e32 v16, v17, v16
	v_cvt_pk_bf16_f32 v15, v15, v16
	v_lshlrev_b32_e32 v16, 16, v24
	v_and_b32_e32 v17, 0xffff0000, v24
	s_waitcnt lgkmcnt(0)
	v_mul_f32_e32 v16, v18, v16
	v_mul_f32_e32 v17, v19, v17
	v_cvt_pk_bf16_f32 v16, v16, v17
	v_lshlrev_b32_e32 v17, 16, v25
	v_and_b32_e32 v18, 0xffff0000, v25
	v_mul_f32_e32 v17, v20, v17
	v_mul_f32_e32 v18, v21, v18
	v_cvt_pk_bf16_f32 v17, v17, v18
	v_lshlrev_b64 v[18:19], 12, v[38:39]
	v_lshl_add_u64 v[18:19], v[12:13], 0, v[18:19]
	global_store_dwordx4 v[18:19], v[14:17], off sc0 sc1
	v_lshl_or_b32 v18, v3, 3, s5
	v_lshl_add_u32 v3, v3, 9, v54
	ds_read_b128 v[14:17], v3
	v_mov_b32_e32 v19, v2
	v_lshl_add_u64 v[22:23], v[18:19], 0, s[66:67]
	ds_read_b128 v[18:21], v3 offset:16
	s_waitcnt vmcnt(7)
	v_lshlrev_b32_e32 v3, 16, v26
	s_waitcnt lgkmcnt(1)
	v_mul_f32_e32 v3, v14, v3
	v_and_b32_e32 v14, 0xffff0000, v26
	v_mul_f32_e32 v14, v15, v14
	v_cvt_pk_bf16_f32 v14, v3, v14
	v_lshlrev_b32_e32 v3, 16, v27
	v_and_b32_e32 v15, 0xffff0000, v27
	v_mul_f32_e32 v3, v16, v3
	v_mul_f32_e32 v15, v17, v15
	v_cvt_pk_bf16_f32 v15, v3, v15
	v_lshlrev_b32_e32 v3, 16, v28
	v_and_b32_e32 v16, 0xffff0000, v28
	s_waitcnt lgkmcnt(0)
	v_mul_f32_e32 v3, v18, v3
	v_mul_f32_e32 v16, v19, v16
	v_cvt_pk_bf16_f32 v16, v3, v16
	v_lshlrev_b32_e32 v3, 16, v29
	v_and_b32_e32 v17, 0xffff0000, v29
	v_mul_f32_e32 v3, v20, v3
	v_mul_f32_e32 v17, v21, v17
	v_lshlrev_b64 v[18:19], 12, v[22:23]
	v_cvt_pk_bf16_f32 v17, v3, v17
	v_lshl_add_u64 v[18:19], v[12:13], 0, v[18:19]
	v_lshrrev_b32_e32 v3, 4, v50
	global_store_dwordx4 v[18:19], v[14:17], off sc0 sc1
	v_lshl_or_b32 v18, v3, 3, s5
	v_lshl_add_u32 v3, v3, 9, v54
	ds_read_b128 v[14:17], v3
	v_mov_b32_e32 v19, v2
	v_lshl_add_u64 v[22:23], v[18:19], 0, s[66:67]
	ds_read_b128 v[18:21], v3 offset:16
	s_waitcnt vmcnt(7)
	v_lshlrev_b32_e32 v3, 16, v30
	s_waitcnt lgkmcnt(1)
	v_mul_f32_e32 v3, v14, v3
	v_and_b32_e32 v14, 0xffff0000, v30
	v_mul_f32_e32 v14, v15, v14
	v_cvt_pk_bf16_f32 v14, v3, v14
	v_lshlrev_b32_e32 v3, 16, v31
	v_and_b32_e32 v15, 0xffff0000, v31
	v_mul_f32_e32 v3, v16, v3
	v_mul_f32_e32 v15, v17, v15
	v_cvt_pk_bf16_f32 v15, v3, v15
	v_lshlrev_b32_e32 v3, 16, v32
	v_and_b32_e32 v16, 0xffff0000, v32
	s_waitcnt lgkmcnt(0)
	v_mul_f32_e32 v3, v18, v3
	v_mul_f32_e32 v16, v19, v16
	v_cvt_pk_bf16_f32 v16, v3, v16
	v_lshlrev_b32_e32 v3, 16, v33
	v_and_b32_e32 v17, 0xffff0000, v33
	v_mul_f32_e32 v3, v20, v3
	v_mul_f32_e32 v17, v21, v17
	v_lshlrev_b64 v[18:19], 12, v[22:23]
	v_cvt_pk_bf16_f32 v17, v3, v17
	v_lshl_add_u64 v[18:19], v[12:13], 0, v[18:19]
	v_lshrrev_b32_e32 v3, 4, v51
	global_store_dwordx4 v[18:19], v[14:17], off sc0 sc1
	v_lshl_or_b32 v18, v3, 3, s5
	v_lshl_add_u32 v3, v3, 9, v54
	ds_read_b128 v[14:17], v3
	v_mov_b32_e32 v19, v2
	v_lshl_add_u64 v[22:23], v[18:19], 0, s[66:67]
	ds_read_b128 v[18:21], v3 offset:16
	s_waitcnt vmcnt(7)
	v_lshlrev_b32_e32 v3, 16, v34
	s_waitcnt lgkmcnt(1)
	v_mul_f32_e32 v3, v14, v3
	v_and_b32_e32 v14, 0xffff0000, v34
	v_mul_f32_e32 v14, v15, v14
	v_cvt_pk_bf16_f32 v14, v3, v14
	v_lshlrev_b32_e32 v3, 16, v35
	v_and_b32_e32 v15, 0xffff0000, v35
	v_mul_f32_e32 v3, v16, v3
	v_mul_f32_e32 v15, v17, v15
	v_cvt_pk_bf16_f32 v15, v3, v15
	v_lshlrev_b32_e32 v3, 16, v36
	v_and_b32_e32 v16, 0xffff0000, v36
	s_waitcnt lgkmcnt(0)
	v_mul_f32_e32 v3, v18, v3
	v_mul_f32_e32 v16, v19, v16
	v_cvt_pk_bf16_f32 v16, v3, v16
	v_lshlrev_b32_e32 v3, 16, v37
	v_and_b32_e32 v17, 0xffff0000, v37
	v_mul_f32_e32 v3, v20, v3
	v_mul_f32_e32 v17, v21, v17
	v_lshlrev_b64 v[18:19], 12, v[22:23]
	v_cvt_pk_bf16_f32 v17, v3, v17
	v_lshl_add_u64 v[18:19], v[12:13], 0, v[18:19]
	v_lshrrev_b32_e32 v3, 4, v52
	global_store_dwordx4 v[18:19], v[14:17], off sc0 sc1
	v_lshl_or_b32 v18, v3, 3, s5
	v_lshl_add_u32 v3, v3, 9, v54
	ds_read_b128 v[14:17], v3
	v_mov_b32_e32 v19, v2
	v_lshl_add_u64 v[22:23], v[18:19], 0, s[66:67]
	ds_read_b128 v[18:21], v3 offset:16
	s_waitcnt vmcnt(7)
	v_lshlrev_b32_e32 v3, 16, v8
	v_and_b32_e32 v8, 0xffff0000, v8
	s_waitcnt lgkmcnt(1)
	v_mul_f32_e32 v3, v14, v3
	v_mul_f32_e32 v8, v15, v8
	v_cvt_pk_bf16_f32 v8, v3, v8
	v_lshlrev_b32_e32 v3, 16, v9
	v_and_b32_e32 v9, 0xffff0000, v9
	v_mul_f32_e32 v3, v16, v3
	v_mul_f32_e32 v9, v17, v9
	v_cvt_pk_bf16_f32 v9, v3, v9
	v_lshlrev_b32_e32 v3, 16, v10
	v_and_b32_e32 v10, 0xffff0000, v10
	s_waitcnt lgkmcnt(0)
	v_mul_f32_e32 v3, v18, v3
	v_mul_f32_e32 v10, v19, v10
	v_cvt_pk_bf16_f32 v10, v3, v10
	v_lshlrev_b32_e32 v3, 16, v11
	v_and_b32_e32 v11, 0xffff0000, v11
	v_mul_f32_e32 v3, v20, v3
	v_mul_f32_e32 v11, v21, v11
	v_lshlrev_b64 v[14:15], 12, v[22:23]
	v_cvt_pk_bf16_f32 v11, v3, v11
	v_lshl_add_u64 v[14:15], v[12:13], 0, v[14:15]
	v_lshrrev_b32_e32 v3, 4, v53
	global_store_dwordx4 v[14:15], v[8:11], off sc0 sc1
	v_lshl_or_b32 v14, v3, 3, s5
	v_lshl_add_u32 v3, v3, 9, v54
	ds_read_b128 v[8:11], v3
	v_mov_b32_e32 v15, v2
	v_lshl_add_u64 v[18:19], v[14:15], 0, s[66:67]
	ds_read_b128 v[14:17], v3 offset:16
	s_waitcnt vmcnt(7)
	v_lshlrev_b32_e32 v3, 16, v4
	v_and_b32_e32 v4, 0xffff0000, v4
	s_waitcnt lgkmcnt(1)
	v_mul_f32_e32 v3, v8, v3
	v_mul_f32_e32 v4, v9, v4
	v_cvt_pk_bf16_f32 v4, v3, v4
	v_lshlrev_b32_e32 v3, 16, v5
	v_and_b32_e32 v5, 0xffff0000, v5
	v_mul_f32_e32 v3, v10, v3
	v_mul_f32_e32 v5, v11, v5
	v_cvt_pk_bf16_f32 v5, v3, v5
	v_lshlrev_b32_e32 v3, 16, v6
	v_and_b32_e32 v6, 0xffff0000, v6
	s_waitcnt lgkmcnt(0)
	v_mul_f32_e32 v3, v14, v3
	v_mul_f32_e32 v6, v15, v6
	v_cvt_pk_bf16_f32 v6, v3, v6
	v_lshlrev_b32_e32 v3, 16, v7
	v_and_b32_e32 v7, 0xffff0000, v7
	v_lshlrev_b64 v[8:9], 12, v[18:19]
	v_mul_f32_e32 v7, v17, v7
	v_lshl_add_u64 v[8:9], v[12:13], 0, v[8:9]
	v_mul_f32_e32 v3, v16, v3
	v_cvt_pk_bf16_f32 v7, v3, v7
	global_store_dwordx4 v[8:9], v[4:7], off sc0 sc1
	s_barrier
	s_mov_b64 s[0:1], 0

.LBB0_529:
	v_add_u32_e32 v28, s1, v27
	s_waitcnt vmcnt(21)
	ds_read_b128 v[30:33], v28 offset:16384
	s_waitcnt vmcnt(19)
	ds_read_b128 v[34:37], v28 offset:16400
	s_add_i32 s5, s0, 1
	s_add_i32 s4, s1, s3
	s_waitcnt vmcnt(18)
	v_xor_b32_e32 v38, s5, v20
	s_waitcnt vmcnt(14)
	v_lshl_add_u32 v46, v38, 4, s4
	s_waitcnt lgkmcnt(1)
	v_mov_b32_e32 v38, v31
	v_mov_b32_e32 v39, v32
	v_mov_b32_e32 v40, v30
	v_mov_b32_e32 v41, v33
	s_waitcnt lgkmcnt(0)
	v_mov_b32_e32 v42, v36
	v_mov_b32_e32 v43, v34
	v_mov_b32_e32 v44, v37
	v_mov_b32_e32 v45, v35
	v_pk_add_f32 v[38:39], v[38:39], v[40:41]
	v_pk_add_f32 v[40:41], v[42:43], v[44:45]
	v_add_f32_e32 v38, v38, v39
	v_add_f32_e32 v38, v38, v41
	v_add_f32_e32 v38, v40, v38
	ds_bpermute_b32 v39, v21, v38
	v_xor_b32_e32 v29, s0, v20
	v_lshl_add_u32 v29, v29, 4, s4
	s_add_i32 s0, s0, 2
	s_addk_i32 s1, 0x1000
	s_waitcnt lgkmcnt(0)
	v_add_f32_e32 v38, v38, v39
	ds_bpermute_b32 v39, v22, v38
	s_cmp_lg_u32 s1, 0
	s_waitcnt lgkmcnt(0)
	v_add_f32_e32 v38, v38, v39
	ds_bpermute_b32 v39, v23, v38
	s_waitcnt lgkmcnt(0)
	v_add_f32_e32 v38, v38, v39
	ds_bpermute_b32 v39, v24, v38
	s_waitcnt lgkmcnt(0)
	v_add_f32_e32 v38, v38, v39
	ds_bpermute_b32 v39, v25, v38
	s_waitcnt lgkmcnt(0)
	v_add_f32_e32 v38, v38, v39
	ds_bpermute_b32 v39, v26, v38
	s_waitcnt lgkmcnt(0)
	v_add_f32_e32 v38, v38, v39
	v_fmamk_f32 v33, v38, 0xbb000000, v33
	v_fmac_f32_e32 v31, 0xbb000000, v38
	v_fmamk_f32 v35, v38, 0xbb000000, v35
	v_fmamk_f32 v34, v38, 0xbb000000, v34
	v_fmamk_f32 v37, v38, 0xbb000000, v37
	v_fmac_f32_e32 v36, 0xbb000000, v38
	v_fmamk_f32 v32, v38, 0xbb000000, v32
	v_fmamk_f32 v30, v38, 0xbb000000, v30
	v_mul_f32_e32 v44, v31, v31
	v_mul_f32_e32 v45, v33, v33
	v_pk_mul_f32 v[38:39], v[36:37], v[36:37]
	v_pk_mul_f32 v[40:41], v[34:35], v[34:35]
	v_fmac_f32_e32 v44, v30, v30
	v_fmac_f32_e32 v45, v32, v32
	v_mov_b32_e32 v42, v38
	v_mov_b32_e32 v43, v40
	v_mov_b32_e32 v40, v39
	v_add_f32_e32 v44, v44, v45
	v_pk_add_f32 v[38:39], v[42:43], v[40:41]
	s_nop 0
	v_add_f32_e32 v39, v39, v44
	v_add_f32_e32 v38, v38, v39
	ds_bpermute_b32 v39, v21, v38
	s_waitcnt lgkmcnt(0)
	v_add_f32_e32 v38, v38, v39
	ds_bpermute_b32 v39, v22, v38
	s_waitcnt lgkmcnt(0)
	v_add_f32_e32 v38, v38, v39
	ds_bpermute_b32 v39, v23, v38
	s_waitcnt lgkmcnt(0)
	v_add_f32_e32 v38, v38, v39
	ds_bpermute_b32 v39, v24, v38
	s_waitcnt lgkmcnt(0)
	v_add_f32_e32 v38, v38, v39
	ds_bpermute_b32 v39, v25, v38
	s_waitcnt lgkmcnt(0)
	v_add_f32_e32 v38, v38, v39
	ds_bpermute_b32 v39, v26, v38
	s_waitcnt lgkmcnt(0)
	v_add_f32_e32 v38, v38, v39
	v_fmamk_f32 v38, v38, 0x3b000000, v204
	v_mul_f32_e32 v39, 0x4f800000, v38
	v_cmp_gt_f32_e32 vcc, s18, v38
	s_nop 1
	v_cndmask_b32_e32 v38, v38, v39, vcc
	v_sqrt_f32_e32 v39, v38
	s_nop 0
	v_add_u32_e32 v40, -1, v39
	v_add_u32_e32 v41, 1, v39
	v_fma_f32 v42, -v40, v39, v38
	v_fma_f32 v43, -v41, v39, v38
	v_cmp_ge_f32_e64 s[6:7], 0, v42
	s_nop 1
	v_cndmask_b32_e64 v39, v39, v40, s[6:7]
	v_cmp_lt_f32_e64 s[6:7], 0, v43
	s_nop 1
	v_cndmask_b32_e64 v39, v39, v41, s[6:7]
	v_mul_f32_e32 v40, 0x37800000, v39
	v_cndmask_b32_e32 v39, v39, v40, vcc
	v_cmp_class_f32_e32 vcc, v38, v205
	s_nop 1
	v_cndmask_b32_e32 v38, v39, v38, vcc
	v_div_scale_f32 v39, s[4:5], v38, v38, 1.0
	v_rcp_f32_e32 v41, v39
	v_div_scale_f32 v40, vcc, 1.0, v38, 1.0
	v_fma_f32 v42, -v39, v41, 1.0
	v_fmac_f32_e32 v41, v42, v41
	v_mul_f32_e32 v42, v40, v41
	v_fma_f32 v43, -v39, v42, v40
	v_fmac_f32_e32 v42, v43, v41
	v_fma_f32 v39, -v39, v42, v40
	v_div_fmas_f32 v39, v39, v41, v42
	v_div_fixup_f32 v38, v39, v38, 1.0
	v_pk_mul_f32 v[30:31], v[30:31], v[38:39] op_sel_hi:[1,0]
	v_pk_mul_f32 v[32:33], v[32:33], v[38:39] op_sel_hi:[1,0]
	v_pk_mul_f32 v[34:35], v[34:35], v[38:39] op_sel_hi:[1,0]
	v_pk_mul_f32 v[36:37], v[36:37], v[38:39] op_sel_hi:[1,0]
	s_waitcnt vmcnt(0)
	v_pk_fma_f32 v[32:33], v[10:11], v[32:33], v[18:19]
	v_pk_fma_f32 v[30:31], v[8:9], v[30:31], v[16:17]
	v_pk_fma_f32 v[36:37], v[6:7], v[36:37], v[14:15]
	v_pk_fma_f32 v[34:35], v[4:5], v[34:35], v[12:13]
	v_mul_f32_e32 v38, 0xbfb8aa3b, v30
	v_mul_f32_e32 v40, 0xbfb8aa3b, v31
	v_mul_f32_e32 v42, 0xbfb8aa3b, v32
	v_mul_f32_e32 v44, 0xbfb8aa3b, v33
	v_mul_f32_e32 v39, 0xbfb8aa3b, v34
	v_mul_f32_e32 v41, 0xbfb8aa3b, v35
	v_mul_f32_e32 v43, 0xbfb8aa3b, v36
	v_mul_f32_e32 v45, 0xbfb8aa3b, v37
	v_exp_f32_e32 v38, v38
	v_exp_f32_e32 v40, v40
	v_exp_f32_e32 v42, v42
	v_exp_f32_e32 v44, v44
	v_exp_f32_e32 v39, v39
	v_exp_f32_e32 v41, v41
	v_exp_f32_e32 v43, v43
	v_exp_f32_e32 v45, v45
	v_add_f32_e32 v38, 1.0, v38
	v_add_f32_e32 v40, 1.0, v40
	v_add_f32_e32 v42, 1.0, v42
	v_add_f32_e32 v44, 1.0, v44
	v_add_f32_e32 v39, 1.0, v39
	v_add_f32_e32 v41, 1.0, v41
	v_add_f32_e32 v43, 1.0, v43
	v_add_f32_e32 v45, 1.0, v45
	v_rcp_f32_e32 v38, v38
	v_rcp_f32_e32 v40, v40
	v_rcp_f32_e32 v42, v42
	v_rcp_f32_e32 v44, v44
	v_rcp_f32_e32 v39, v39
	v_rcp_f32_e32 v41, v41
	v_rcp_f32_e32 v43, v43
	v_rcp_f32_e32 v45, v45
	v_mul_f32_e32 v30, v30, v38
	v_mul_f32_e32 v31, v31, v40
	v_mul_f32_e32 v32, v32, v42
	v_mul_f32_e32 v33, v33, v44
	v_mul_f32_e32 v34, v34, v39
	v_mul_f32_e32 v35, v35, v41
	v_mul_f32_e32 v36, v36, v43
	v_mul_f32_e32 v37, v37, v45
	v_cvt_pk_bf16_f32 v30, v30, v31
	v_cvt_pk_bf16_f32 v31, v32, v33
	v_cvt_pk_bf16_f32 v32, v34, v35
	v_cvt_pk_bf16_f32 v33, v36, v37
	ds_write_b128 v29, v[30:33] offset:16384
	ds_read_b128 v[30:33], v28 offset:18432
	ds_read_b128 v[34:37], v28 offset:18448
	s_waitcnt lgkmcnt(1)
	v_mov_b32_e32 v28, v31
	v_mov_b32_e32 v29, v32
	v_mov_b32_e32 v38, v30
	v_mov_b32_e32 v39, v33
	s_waitcnt lgkmcnt(0)
	v_mov_b32_e32 v40, v36
	v_mov_b32_e32 v41, v34
	v_mov_b32_e32 v42, v37
	v_mov_b32_e32 v43, v35
	v_pk_add_f32 v[28:29], v[28:29], v[38:39]
	v_pk_add_f32 v[38:39], v[40:41], v[42:43]
	v_add_f32_e32 v28, v28, v29
	v_add_f32_e32 v28, v28, v39
	v_add_f32_e32 v28, v38, v28
	ds_bpermute_b32 v29, v21, v28
	s_waitcnt lgkmcnt(0)
	v_add_f32_e32 v28, v28, v29
	ds_bpermute_b32 v29, v22, v28
	s_waitcnt lgkmcnt(0)
	v_add_f32_e32 v28, v28, v29
	ds_bpermute_b32 v29, v23, v28
	s_waitcnt lgkmcnt(0)
	v_add_f32_e32 v28, v28, v29
	ds_bpermute_b32 v29, v24, v28
	s_waitcnt lgkmcnt(0)
	v_add_f32_e32 v28, v28, v29
	ds_bpermute_b32 v29, v25, v28
	s_waitcnt lgkmcnt(0)
	v_add_f32_e32 v28, v28, v29
	ds_bpermute_b32 v29, v26, v28
	s_waitcnt lgkmcnt(0)
	v_add_f32_e32 v38, v28, v29
	v_fmamk_f32 v28, v38, 0xbb000000, v32
	v_fmamk_f32 v29, v38, 0xbb000000, v33
	v_fmac_f32_e32 v31, 0xbb000000, v38
	v_fmamk_f32 v33, v38, 0xbb000000, v35
	v_fmamk_f32 v32, v38, 0xbb000000, v34
	v_fmamk_f32 v37, v38, 0xbb000000, v37
	v_fmac_f32_e32 v36, 0xbb000000, v38
	v_fmamk_f32 v30, v38, 0xbb000000, v30
	v_mul_f32_e32 v42, v31, v31
	v_mul_f32_e32 v43, v29, v29
	v_pk_mul_f32 v[34:35], v[36:37], v[36:37]
	v_pk_mul_f32 v[38:39], v[32:33], v[32:33]
	v_fmac_f32_e32 v42, v30, v30
	v_fmac_f32_e32 v43, v28, v28
	v_mov_b32_e32 v40, v34
	v_mov_b32_e32 v41, v38
	v_mov_b32_e32 v38, v35
	v_add_f32_e32 v42, v42, v43
	v_pk_add_f32 v[34:35], v[40:41], v[38:39]
	s_nop 0
	v_add_f32_e32 v35, v35, v42
	v_add_f32_e32 v34, v34, v35
	ds_bpermute_b32 v35, v21, v34
	s_waitcnt lgkmcnt(0)
	v_add_f32_e32 v34, v34, v35
	ds_bpermute_b32 v35, v22, v34
	s_waitcnt lgkmcnt(0)
	v_add_f32_e32 v34, v34, v35
	ds_bpermute_b32 v35, v23, v34
	s_waitcnt lgkmcnt(0)
	v_add_f32_e32 v34, v34, v35
	ds_bpermute_b32 v35, v24, v34
	s_waitcnt lgkmcnt(0)
	v_add_f32_e32 v34, v34, v35
	ds_bpermute_b32 v35, v25, v34
	s_waitcnt lgkmcnt(0)
	v_add_f32_e32 v34, v34, v35
	ds_bpermute_b32 v35, v26, v34
	s_waitcnt lgkmcnt(0)
	v_add_f32_e32 v34, v34, v35
	v_fmamk_f32 v34, v34, 0x3b000000, v204
	v_mul_f32_e32 v35, 0x4f800000, v34
	v_cmp_gt_f32_e32 vcc, s18, v34
	s_nop 1
	v_cndmask_b32_e32 v34, v34, v35, vcc
	v_sqrt_f32_e32 v35, v34
	s_nop 0
	v_add_u32_e32 v38, -1, v35
	v_add_u32_e32 v39, 1, v35
	v_fma_f32 v40, -v38, v35, v34
	v_fma_f32 v41, -v39, v35, v34
	v_cmp_ge_f32_e64 s[6:7], 0, v40
	s_nop 1
	v_cndmask_b32_e64 v35, v35, v38, s[6:7]
	v_cmp_lt_f32_e64 s[6:7], 0, v41
	s_nop 1
	v_cndmask_b32_e64 v35, v35, v39, s[6:7]
	v_mul_f32_e32 v38, 0x37800000, v35
	v_cndmask_b32_e32 v35, v35, v38, vcc
	v_cmp_class_f32_e32 vcc, v34, v205
	s_nop 1
	v_cndmask_b32_e32 v34, v35, v34, vcc
	v_div_scale_f32 v35, s[4:5], v34, v34, 1.0
	v_rcp_f32_e32 v39, v35
	v_div_scale_f32 v38, vcc, 1.0, v34, 1.0
	v_fma_f32 v40, -v35, v39, 1.0
	v_fmac_f32_e32 v39, v40, v39
	v_mul_f32_e32 v40, v38, v39
	v_fma_f32 v41, -v35, v40, v38
	v_fmac_f32_e32 v40, v41, v39
	v_fma_f32 v35, -v35, v40, v38
	v_div_fmas_f32 v35, v35, v39, v40
	v_div_fixup_f32 v34, v35, v34, 1.0
	v_pk_mul_f32 v[30:31], v[30:31], v[34:35] op_sel_hi:[1,0]
	v_pk_mul_f32 v[28:29], v[28:29], v[34:35] op_sel_hi:[1,0]
	v_pk_mul_f32 v[32:33], v[32:33], v[34:35] op_sel_hi:[1,0]
	v_pk_mul_f32 v[34:35], v[36:37], v[34:35] op_sel_hi:[1,0]
	v_pk_fma_f32 v[28:29], v[10:11], v[28:29], v[18:19]
	v_pk_fma_f32 v[30:31], v[8:9], v[30:31], v[16:17]
	v_pk_fma_f32 v[34:35], v[6:7], v[34:35], v[14:15]
	v_pk_fma_f32 v[32:33], v[4:5], v[32:33], v[12:13]
	v_mul_f32_e32 v36, 0xbfb8aa3b, v30
	v_mul_f32_e32 v38, 0xbfb8aa3b, v31
	v_mul_f32_e32 v42, 0xbfb8aa3b, v29
	v_mul_f32_e32 v37, 0xbfb8aa3b, v32
	v_mul_f32_e32 v39, 0xbfb8aa3b, v33
	v_mul_f32_e32 v40, 0xbfb8aa3b, v28
	v_mul_f32_e32 v41, 0xbfb8aa3b, v34
	v_mul_f32_e32 v43, 0xbfb8aa3b, v35
	v_exp_f32_e32 v36, v36
	v_exp_f32_e32 v38, v38
	v_exp_f32_e32 v42, v42
	v_exp_f32_e32 v37, v37
	v_exp_f32_e32 v39, v39
	v_exp_f32_e32 v40, v40
	v_exp_f32_e32 v41, v41
	v_exp_f32_e32 v43, v43
	v_add_f32_e32 v36, 1.0, v36
	v_add_f32_e32 v38, 1.0, v38
	v_add_f32_e32 v42, 1.0, v42
	v_add_f32_e32 v37, 1.0, v37
	v_add_f32_e32 v39, 1.0, v39
	v_add_f32_e32 v40, 1.0, v40
	v_add_f32_e32 v41, 1.0, v41
	v_add_f32_e32 v43, 1.0, v43
	v_rcp_f32_e32 v36, v36
	v_rcp_f32_e32 v38, v38
	v_rcp_f32_e32 v42, v42
	v_rcp_f32_e32 v37, v37
	v_rcp_f32_e32 v39, v39
	v_rcp_f32_e32 v40, v40
	v_rcp_f32_e32 v41, v41
	v_rcp_f32_e32 v43, v43
	v_mul_f32_e32 v30, v30, v36
	v_mul_f32_e32 v31, v31, v38
	v_mul_f32_e32 v29, v29, v42
	v_mul_f32_e32 v32, v32, v37
	v_mul_f32_e32 v33, v33, v39
	v_mul_f32_e32 v36, v28, v40
	v_mul_f32_e32 v34, v34, v41
	v_mul_f32_e32 v35, v35, v43
	v_cvt_pk_bf16_f32 v28, v30, v31
	v_cvt_pk_bf16_f32 v29, v36, v29
	v_cvt_pk_bf16_f32 v30, v32, v33
	v_cvt_pk_bf16_f32 v31, v34, v35
	ds_write_b128 v46, v[28:31] offset:18432
	s_cbranch_scc1 .LBB0_529
	s_load_dwordx16 s[72:87], s[52:53], 0x40
	v_and_b32_e32 v12, 31, v3
	v_lshrrev_b32_e32 v186, 5, v20
	v_lshlrev_b32_e32 v6, 4, v186
	v_mov_b32_e32 v7, v2
	s_waitcnt lgkmcnt(0)
	s_add_u32 s6, s80, s68
	s_addc_u32 s7, s81, s69
	s_andn2_b32 s2, s2, 63
	v_or_b32_e32 v180, s2, v12
	v_ashrrev_i32_e32 v181, 31, v180
	v_lshlrev_b64 v[4:5], 10, v[180:181]
	v_lshl_add_u64 v[4:5], s[66:67], 0, v[4:5]
	v_lshl_add_u64 v[4:5], v[4:5], 0, v[6:7]
	s_mov_b64 s[0:1], 0x2800000
	v_lshl_add_u64 v[182:183], v[4:5], 0, s[0:1]
	s_mov_b32 s0, 0x2800000
	v_add_co_u32_e32 v8, vcc, s0, v4
	s_mov_b32 s0, 0x2808000
	s_nop 0
	v_addc_co_u32_e32 v9, vcc, 0, v5, vcc
	v_add_co_u32_e32 v184, vcc, s0, v4
	s_nop 1
	v_addc_co_u32_e32 v185, vcc, 0, v5, vcc
	s_barrier
	global_load_dwordx4 v[4:7], v[184:185], off
	global_load_dwordx4 v[96:99], v[184:185], off offset:32
	global_load_dwordx4 v[100:103], v[182:183], off offset:32
	global_load_dwordx4 v[104:107], v[182:183], off offset:64
	global_load_dwordx4 v[108:111], v[184:185], off offset:64
	global_load_dwordx4 v[116:119], v[184:185], off offset:96
	global_load_dwordx4 v[124:127], v[182:183], off offset:96
	global_load_dwordx4 v[132:135], v[182:183], off offset:128
	global_load_dwordx4 v[136:139], v[184:185], off offset:128
	global_load_dwordx4 v[140:143], v[184:185], off offset:160
	global_load_dwordx4 v[152:155], v[182:183], off offset:160
	global_load_dwordx4 v[156:159], v[182:183], off offset:192
	s_nop 0
	global_load_dwordx4 v[8:11], v[8:9], off
	s_nop 0
	global_load_dwordx4 v[160:163], v[182:183], off offset:224
	global_load_dwordx4 v[172:175], v[184:185], off offset:192
	global_load_dwordx4 v[176:179], v[184:185], off offset:224
	global_load_dwordx4 v[190:193], v[182:183], off offset:256
	global_load_dwordx4 v[164:167], v[182:183], off offset:288
	global_load_dwordx4 v[198:201], v[184:185], off offset:256
	global_load_dwordx4 v[168:171], v[184:185], off offset:288
	global_load_dwordx4 v[144:147], v[182:183], off offset:320
	global_load_dwordx4 v[120:123], v[182:183], off offset:352
	global_load_dwordx4 v[148:151], v[184:185], off offset:320
	global_load_dwordx4 v[128:131], v[184:185], off offset:352
	global_load_dwordx4 v[92:95], v[182:183], off offset:384
	global_load_dwordx4 v[84:87], v[182:183], off offset:416
	global_load_dwordx4 v[112:115], v[184:185], off offset:384
	global_load_dwordx4 v[88:91], v[184:185], off offset:416
	global_load_dwordx4 v[76:79], v[182:183], off offset:448
	global_load_dwordx4 v[68:71], v[182:183], off offset:480
	global_load_dwordx4 v[80:83], v[184:185], off offset:448
	global_load_dwordx4 v[72:75], v[184:185], off offset:480
	v_lshl_add_u32 v187, v12, 11, 0
	v_bitop3_b32 v12, v186, v3, 15 bitop3:0x78
	v_lshlrev_b32_e32 v16, 4, v12
	v_add_u32_e32 v188, 0x10000, v187
	v_add_u32_e32 v12, v187, v16
	v_add_u32_e32 v16, v188, v16
	ds_read_b128 v[12:15], v12
	ds_read_b128 v[16:19], v16
	v_and_b32_e32 v189, 15, v3
	v_bitop3_b32 v197, v186, v189, 2 bitop3:0x36
	v_lshlrev_b32_e32 v197, 4, v197
	v_add_u32_e32 v202, v187, v197
	v_add_u32_e32 v197, v188, v197
	ds_read_b128 v[210:213], v202
	ds_read_b128 v[214:217], v197
	s_waitcnt vmcnt(19) lgkmcnt(3)
	v_mfma_f32_32x32x16_bf16 v[52:67], v[12:15], v[8:11], 0
	v_mfma_f32_32x32x16_bf16 v[20:35], v[12:15], v[4:7], 0
	s_waitcnt lgkmcnt(2)
	v_mfma_f32_32x32x16_bf16 v[36:51], v[16:19], v[8:11], 0
	v_mfma_f32_32x32x16_bf16 v[4:19], v[16:19], v[4:7], 0
	s_waitcnt lgkmcnt(1)
	v_mfma_f32_32x32x16_bf16 v[20:35], v[210:213], v[96:99], v[20:35]
	s_waitcnt lgkmcnt(0)
	v_mfma_f32_32x32x16_bf16 v[4:19], v[214:217], v[96:99], v[4:19]
	v_bitop3_b32 v96, v186, v189, 4 bitop3:0x36
	v_mfma_f32_32x32x16_bf16 v[52:67], v[210:213], v[100:103], v[52:67]
	v_mfma_f32_32x32x16_bf16 v[36:51], v[214:217], v[100:103], v[36:51]
	v_lshlrev_b32_e32 v100, 4, v96
	v_add_u32_e32 v96, v187, v100
	ds_read_b128 v[96:99], v96
	v_add_u32_e32 v100, v188, v100
	ds_read_b128 v[100:103], v100
	s_waitcnt lgkmcnt(1)
	v_mfma_f32_32x32x16_bf16 v[52:67], v[96:99], v[104:107], v[52:67]
	v_mfma_f32_32x32x16_bf16 v[20:35], v[96:99], v[108:111], v[20:35]
	v_bitop3_b32 v96, v186, v189, 6 bitop3:0x36
	s_waitcnt lgkmcnt(0)
	v_mfma_f32_32x32x16_bf16 v[36:51], v[100:103], v[104:107], v[36:51]
	v_mfma_f32_32x32x16_bf16 v[4:19], v[100:103], v[108:111], v[4:19]
	v_lshlrev_b32_e32 v100, 4, v96
	v_add_u32_e32 v96, v187, v100
	ds_read_b128 v[96:99], v96
	v_add_u32_e32 v100, v188, v100
	ds_read_b128 v[100:103], v100
	s_waitcnt lgkmcnt(1)
	v_mfma_f32_32x32x16_bf16 v[52:67], v[96:99], v[124:127], v[52:67]
	v_mfma_f32_32x32x16_bf16 v[20:35], v[96:99], v[116:119], v[20:35]
	v_bitop3_b32 v96, v186, v189, 8 bitop3:0x36
	s_waitcnt lgkmcnt(0)
	v_mfma_f32_32x32x16_bf16 v[36:51], v[100:103], v[124:127], v[36:51]
	v_mfma_f32_32x32x16_bf16 v[4:19], v[100:103], v[116:119], v[4:19]
	v_lshlrev_b32_e32 v100, 4, v96
	v_add_u32_e32 v96, v187, v100
	ds_read_b128 v[96:99], v96
	v_add_u32_e32 v100, v188, v100
	ds_read_b128 v[100:103], v100
	s_waitcnt lgkmcnt(1)
	v_mfma_f32_32x32x16_bf16 v[52:67], v[96:99], v[132:135], v[52:67]
	v_mfma_f32_32x32x16_bf16 v[20:35], v[96:99], v[136:139], v[20:35]
	v_bitop3_b32 v96, v186, v189, 10 bitop3:0x36
	s_waitcnt lgkmcnt(0)
	v_mfma_f32_32x32x16_bf16 v[36:51], v[100:103], v[132:135], v[36:51]
	v_mfma_f32_32x32x16_bf16 v[4:19], v[100:103], v[136:139], v[4:19]
	v_lshlrev_b32_e32 v100, 4, v96
	v_add_u32_e32 v96, v187, v100
	ds_read_b128 v[96:99], v96
	v_add_u32_e32 v100, v188, v100
	ds_read_b128 v[100:103], v100
	s_waitcnt lgkmcnt(1)
	v_mfma_f32_32x32x16_bf16 v[52:67], v[96:99], v[152:155], v[52:67]
	v_mfma_f32_32x32x16_bf16 v[20:35], v[96:99], v[140:143], v[20:35]
	v_bitop3_b32 v96, v186, v189, 12 bitop3:0x36
	s_waitcnt lgkmcnt(0)
	v_mfma_f32_32x32x16_bf16 v[36:51], v[100:103], v[152:155], v[36:51]
	v_mfma_f32_32x32x16_bf16 v[4:19], v[100:103], v[140:143], v[4:19]
	v_lshlrev_b32_e32 v100, 4, v96
	v_add_u32_e32 v96, v187, v100
	ds_read_b128 v[96:99], v96
	v_add_u32_e32 v100, v188, v100
	ds_read_b128 v[100:103], v100
	s_waitcnt lgkmcnt(1)
	v_mfma_f32_32x32x16_bf16 v[52:67], v[96:99], v[156:159], v[52:67]
	s_waitcnt vmcnt(17)
	v_mfma_f32_32x32x16_bf16 v[20:35], v[96:99], v[172:175], v[20:35]
	v_bitop3_b32 v96, v186, v189, 14 bitop3:0x36
	s_waitcnt lgkmcnt(0)
	v_mfma_f32_32x32x16_bf16 v[36:51], v[100:103], v[156:159], v[36:51]
	v_mfma_f32_32x32x16_bf16 v[4:19], v[100:103], v[172:175], v[4:19]
	v_lshlrev_b32_e32 v100, 4, v96
	v_add_u32_e32 v96, v187, v100
	v_add_u32_e32 v100, v188, v100
	ds_read_b128 v[96:99], v96
	ds_read_b128 v[100:103], v100
	s_waitcnt lgkmcnt(1)
	v_mfma_f32_32x32x16_bf16 v[52:67], v[96:99], v[160:163], v[52:67]
	s_waitcnt vmcnt(16)
	v_mfma_f32_32x32x16_bf16 v[20:35], v[96:99], v[176:179], v[20:35]
	s_waitcnt lgkmcnt(0)
	v_mfma_f32_32x32x16_bf16 v[36:51], v[100:103], v[160:163], v[36:51]
	v_mfma_f32_32x32x16_bf16 v[4:19], v[100:103], v[176:179], v[4:19]
	global_load_dwordx4 v[210:213], v[182:183], off offset:512
	global_load_dwordx4 v[172:175], v[182:183], off offset:544
	global_load_dwordx4 v[214:217], v[184:185], off offset:512
	global_load_dwordx4 v[176:179], v[184:185], off offset:544
	global_load_dwordx4 v[156:159], v[182:183], off offset:576
	global_load_dwordx4 v[140:143], v[182:183], off offset:608
	global_load_dwordx4 v[160:163], v[184:185], off offset:576
	global_load_dwordx4 v[152:155], v[184:185], off offset:608
	global_load_dwordx4 v[132:135], v[182:183], off offset:640
	global_load_dwordx4 v[116:119], v[182:183], off offset:672
	global_load_dwordx4 v[136:139], v[184:185], off offset:640
	global_load_dwordx4 v[124:127], v[184:185], off offset:672
	global_load_dwordx4 v[104:107], v[182:183], off offset:704
	global_load_dwordx4 v[96:99], v[182:183], off offset:736
	global_load_dwordx4 v[108:111], v[184:185], off offset:704
	global_load_dwordx4 v[100:103], v[184:185], off offset:736
	v_bitop3_b32 v197, v186, v189, 16 bitop3:0x36
	v_lshlrev_b32_e32 v197, 4, v197
	v_add_u32_e32 v202, v187, v197
	v_add_u32_e32 v197, v188, v197
	ds_read_b128 v[218:221], v202
	ds_read_b128 v[222:225], v197
	s_waitcnt vmcnt(31) lgkmcnt(1)
	v_mfma_f32_32x32x16_bf16 v[52:67], v[218:221], v[190:193], v[52:67]
	s_waitcnt lgkmcnt(0)
	v_mfma_f32_32x32x16_bf16 v[36:51], v[222:225], v[190:193], v[36:51]
	v_bitop3_b32 v190, v186, v189, 18 bitop3:0x36
	v_lshlrev_b32_e32 v197, 4, v190
	v_add_u32_e32 v190, v187, v197
	v_add_u32_e32 v197, v188, v197
	ds_read_b128 v[190:193], v190
	s_waitcnt vmcnt(29)
	v_mfma_f32_32x32x16_bf16 v[20:35], v[218:221], v[198:201], v[20:35]
	v_mfma_f32_32x32x16_bf16 v[4:19], v[222:225], v[198:201], v[4:19]
	ds_read_b128 v[198:201], v197
	s_waitcnt lgkmcnt(1)
	v_mfma_f32_32x32x16_bf16 v[52:67], v[190:193], v[164:167], v[52:67]
	s_waitcnt lgkmcnt(0)
	v_mfma_f32_32x32x16_bf16 v[36:51], v[198:201], v[164:167], v[36:51]
	v_bitop3_b32 v164, v186, v189, 20 bitop3:0x36
	s_waitcnt vmcnt(28)
	v_mfma_f32_32x32x16_bf16 v[20:35], v[190:193], v[168:171], v[20:35]
	v_mfma_f32_32x32x16_bf16 v[4:19], v[198:201], v[168:171], v[4:19]
	v_lshlrev_b32_e32 v168, 4, v164
	v_add_u32_e32 v164, v187, v168
	v_add_u32_e32 v168, v188, v168
	ds_read_b128 v[164:167], v164
	ds_read_b128 v[168:171], v168
	s_waitcnt vmcnt(27) lgkmcnt(1)
	v_mfma_f32_32x32x16_bf16 v[52:67], v[164:167], v[144:147], v[52:67]
	s_waitcnt lgkmcnt(0)
	v_mfma_f32_32x32x16_bf16 v[36:51], v[168:171], v[144:147], v[36:51]
	v_bitop3_b32 v144, v186, v189, 22 bitop3:0x36
	s_waitcnt vmcnt(25)
	v_mfma_f32_32x32x16_bf16 v[20:35], v[164:167], v[148:151], v[20:35]
	v_mfma_f32_32x32x16_bf16 v[4:19], v[168:171], v[148:151], v[4:19]
	v_lshlrev_b32_e32 v148, 4, v144
	v_add_u32_e32 v144, v187, v148
	v_add_u32_e32 v148, v188, v148
	ds_read_b128 v[144:147], v144
	ds_read_b128 v[148:151], v148
	s_waitcnt lgkmcnt(1)
	v_mfma_f32_32x32x16_bf16 v[52:67], v[144:147], v[120:123], v[52:67]
	s_waitcnt lgkmcnt(0)
	v_mfma_f32_32x32x16_bf16 v[36:51], v[148:151], v[120:123], v[36:51]
	v_bitop3_b32 v120, v186, v189, 24 bitop3:0x36
	s_waitcnt vmcnt(24)
	v_mfma_f32_32x32x16_bf16 v[20:35], v[144:147], v[128:131], v[20:35]
	v_mfma_f32_32x32x16_bf16 v[4:19], v[148:151], v[128:131], v[4:19]
	v_lshlrev_b32_e32 v128, 4, v120
	v_add_u32_e32 v120, v187, v128
	v_add_u32_e32 v128, v188, v128
	ds_read_b128 v[120:123], v120
	ds_read_b128 v[128:131], v128
	s_waitcnt vmcnt(23) lgkmcnt(1)
	v_mfma_f32_32x32x16_bf16 v[52:67], v[120:123], v[92:95], v[52:67]
	s_waitcnt lgkmcnt(0)
	v_mfma_f32_32x32x16_bf16 v[36:51], v[128:131], v[92:95], v[36:51]
	v_bitop3_b32 v92, v186, v189, 26 bitop3:0x36
	s_waitcnt vmcnt(21)
	v_mfma_f32_32x32x16_bf16 v[20:35], v[120:123], v[112:115], v[20:35]
	v_mfma_f32_32x32x16_bf16 v[4:19], v[128:131], v[112:115], v[4:19]
	v_lshlrev_b32_e32 v112, 4, v92
	v_add_u32_e32 v92, v187, v112
	v_add_u32_e32 v112, v188, v112
	ds_read_b128 v[92:95], v92
	ds_read_b128 v[112:115], v112
	s_waitcnt lgkmcnt(1)
	v_mfma_f32_32x32x16_bf16 v[52:67], v[92:95], v[84:87], v[52:67]
	s_waitcnt lgkmcnt(0)
	v_mfma_f32_32x32x16_bf16 v[36:51], v[112:115], v[84:87], v[36:51]
	v_bitop3_b32 v84, v186, v189, 28 bitop3:0x36
	s_waitcnt vmcnt(20)
	v_mfma_f32_32x32x16_bf16 v[20:35], v[92:95], v[88:91], v[20:35]
	v_mfma_f32_32x32x16_bf16 v[4:19], v[112:115], v[88:91], v[4:19]
	v_lshlrev_b32_e32 v88, 4, v84
	v_add_u32_e32 v84, v187, v88
	v_add_u32_e32 v88, v188, v88
	ds_read_b128 v[84:87], v84
	ds_read_b128 v[88:91], v88
	s_waitcnt vmcnt(19) lgkmcnt(1)
	v_mfma_f32_32x32x16_bf16 v[52:67], v[84:87], v[76:79], v[52:67]
	s_waitcnt lgkmcnt(0)
	v_mfma_f32_32x32x16_bf16 v[36:51], v[88:91], v[76:79], v[36:51]
	v_bitop3_b32 v76, v186, v189, 30 bitop3:0x36
	s_waitcnt vmcnt(17)
	v_mfma_f32_32x32x16_bf16 v[20:35], v[84:87], v[80:83], v[20:35]
	v_mfma_f32_32x32x16_bf16 v[4:19], v[88:91], v[80:83], v[4:19]
	v_lshlrev_b32_e32 v80, 4, v76
	v_add_u32_e32 v76, v187, v80
	v_add_u32_e32 v80, v188, v80
	ds_read_b128 v[76:79], v76
	ds_read_b128 v[80:83], v80
	s_waitcnt lgkmcnt(1)
	v_mfma_f32_32x32x16_bf16 v[52:67], v[76:79], v[68:71], v[52:67]
	s_waitcnt vmcnt(16)
	v_mfma_f32_32x32x16_bf16 v[20:35], v[76:79], v[72:75], v[20:35]
	s_waitcnt lgkmcnt(0)
	v_mfma_f32_32x32x16_bf16 v[36:51], v[80:83], v[68:71], v[36:51]
	v_mfma_f32_32x32x16_bf16 v[4:19], v[80:83], v[72:75], v[4:19]
	global_load_dwordx4 v[168:171], v[182:183], off offset:768
	global_load_dwordx4 v[190:193], v[182:183], off offset:800
	global_load_dwordx4 v[198:201], v[184:185], off offset:768
	global_load_dwordx4 v[92:95], v[184:185], off offset:800
	global_load_dwordx4 v[164:167], v[182:183], off offset:832
	global_load_dwordx4 v[144:147], v[182:183], off offset:864
	global_load_dwordx4 v[88:91], v[184:185], off offset:832
	global_load_dwordx4 v[84:87], v[184:185], off offset:864
	global_load_dwordx4 v[148:151], v[182:183], off offset:896
	global_load_dwordx4 v[128:131], v[182:183], off offset:928
	global_load_dwordx4 v[80:83], v[184:185], off offset:896
	global_load_dwordx4 v[76:79], v[184:185], off offset:928
	global_load_dwordx4 v[120:123], v[182:183], off offset:960
	global_load_dwordx4 v[112:115], v[182:183], off offset:992
	global_load_dwordx4 v[72:75], v[184:185], off offset:960
	global_load_dwordx4 v[68:71], v[184:185], off offset:992
	v_bitop3_b32 v182, v186, v189, 32 bitop3:0x36
	v_lshlrev_b32_e32 v197, 4, v182
	v_add_u32_e32 v182, v187, v197
	ds_read_b128 v[182:185], v182
	v_add_u32_e32 v197, v188, v197
	ds_read_b128 v[218:221], v197
	s_waitcnt vmcnt(31) lgkmcnt(1)
	v_mfma_f32_32x32x16_bf16 v[52:67], v[182:185], v[210:213], v[52:67]
	s_waitcnt vmcnt(29)
	v_mfma_f32_32x32x16_bf16 v[20:35], v[182:185], v[214:217], v[20:35]
	v_bitop3_b32 v182, v186, v189, 34 bitop3:0x36
	v_lshlrev_b32_e32 v197, 4, v182
	v_add_u32_e32 v182, v187, v197
	v_add_u32_e32 v197, v188, v197
	ds_read_b128 v[182:185], v182
	s_waitcnt lgkmcnt(1)
	v_mfma_f32_32x32x16_bf16 v[36:51], v[218:221], v[210:213], v[36:51]
	ds_read_b128 v[210:213], v197
	v_mfma_f32_32x32x16_bf16 v[4:19], v[218:221], v[214:217], v[4:19]
	s_waitcnt lgkmcnt(1)
	v_mfma_f32_32x32x16_bf16 v[52:67], v[182:185], v[172:175], v[52:67]
	s_waitcnt lgkmcnt(0)
	v_mfma_f32_32x32x16_bf16 v[36:51], v[210:213], v[172:175], v[36:51]
	v_bitop3_b32 v172, v186, v189, 36 bitop3:0x36
	s_waitcnt vmcnt(28)
	v_mfma_f32_32x32x16_bf16 v[20:35], v[182:185], v[176:179], v[20:35]
	v_mfma_f32_32x32x16_bf16 v[4:19], v[210:213], v[176:179], v[4:19]
	v_lshlrev_b32_e32 v176, 4, v172
	v_add_u32_e32 v172, v187, v176
	v_add_u32_e32 v176, v188, v176
	ds_read_b128 v[172:175], v172
	ds_read_b128 v[176:179], v176
	s_waitcnt vmcnt(27) lgkmcnt(1)
	v_mfma_f32_32x32x16_bf16 v[52:67], v[172:175], v[156:159], v[52:67]
	s_waitcnt lgkmcnt(0)
	v_mfma_f32_32x32x16_bf16 v[36:51], v[176:179], v[156:159], v[36:51]
	v_bitop3_b32 v156, v186, v189, 38 bitop3:0x36
	s_waitcnt vmcnt(25)
	v_mfma_f32_32x32x16_bf16 v[20:35], v[172:175], v[160:163], v[20:35]
	v_mfma_f32_32x32x16_bf16 v[4:19], v[176:179], v[160:163], v[4:19]
	v_lshlrev_b32_e32 v160, 4, v156
	v_add_u32_e32 v156, v187, v160
	v_add_u32_e32 v160, v188, v160
	ds_read_b128 v[156:159], v156
	ds_read_b128 v[160:163], v160
	s_waitcnt lgkmcnt(1)
	v_mfma_f32_32x32x16_bf16 v[52:67], v[156:159], v[140:143], v[52:67]
	s_waitcnt lgkmcnt(0)
	v_mfma_f32_32x32x16_bf16 v[36:51], v[160:163], v[140:143], v[36:51]
	v_bitop3_b32 v140, v186, v189, 40 bitop3:0x36
	s_waitcnt vmcnt(24)
	v_mfma_f32_32x32x16_bf16 v[20:35], v[156:159], v[152:155], v[20:35]
	v_mfma_f32_32x32x16_bf16 v[4:19], v[160:163], v[152:155], v[4:19]
	v_lshlrev_b32_e32 v152, 4, v140
	v_add_u32_e32 v140, v187, v152
	v_add_u32_e32 v152, v188, v152
	ds_read_b128 v[140:143], v140
	ds_read_b128 v[152:155], v152
	s_waitcnt vmcnt(23) lgkmcnt(1)
	v_mfma_f32_32x32x16_bf16 v[52:67], v[140:143], v[132:135], v[52:67]
	s_waitcnt lgkmcnt(0)
	v_mfma_f32_32x32x16_bf16 v[36:51], v[152:155], v[132:135], v[36:51]
	v_bitop3_b32 v132, v186, v189, 42 bitop3:0x36
	s_waitcnt vmcnt(21)
	v_mfma_f32_32x32x16_bf16 v[20:35], v[140:143], v[136:139], v[20:35]
	v_mfma_f32_32x32x16_bf16 v[4:19], v[152:155], v[136:139], v[4:19]
	v_lshlrev_b32_e32 v136, 4, v132
	v_add_u32_e32 v132, v187, v136
	v_add_u32_e32 v136, v188, v136
	ds_read_b128 v[132:135], v132
	ds_read_b128 v[136:139], v136
	s_waitcnt lgkmcnt(1)
	v_mfma_f32_32x32x16_bf16 v[52:67], v[132:135], v[116:119], v[52:67]
	s_waitcnt lgkmcnt(0)
	v_mfma_f32_32x32x16_bf16 v[36:51], v[136:139], v[116:119], v[36:51]
	v_bitop3_b32 v116, v186, v189, 44 bitop3:0x36
	s_waitcnt vmcnt(20)
	v_mfma_f32_32x32x16_bf16 v[20:35], v[132:135], v[124:127], v[20:35]
	v_mfma_f32_32x32x16_bf16 v[4:19], v[136:139], v[124:127], v[4:19]
	v_lshlrev_b32_e32 v124, 4, v116
	v_add_u32_e32 v116, v187, v124
	v_add_u32_e32 v124, v188, v124
	ds_read_b128 v[116:119], v116
	ds_read_b128 v[124:127], v124
	s_waitcnt vmcnt(19) lgkmcnt(1)
	v_mfma_f32_32x32x16_bf16 v[52:67], v[116:119], v[104:107], v[52:67]
	s_waitcnt lgkmcnt(0)
	v_mfma_f32_32x32x16_bf16 v[36:51], v[124:127], v[104:107], v[36:51]
	v_bitop3_b32 v104, v186, v189, 46 bitop3:0x36
	s_waitcnt vmcnt(17)
	v_mfma_f32_32x32x16_bf16 v[20:35], v[116:119], v[108:111], v[20:35]
	v_mfma_f32_32x32x16_bf16 v[4:19], v[124:127], v[108:111], v[4:19]
	v_lshlrev_b32_e32 v108, 4, v104
	v_add_u32_e32 v104, v187, v108
	v_add_u32_e32 v108, v188, v108
	ds_read_b128 v[104:107], v104
	ds_read_b128 v[108:111], v108
	s_waitcnt lgkmcnt(1)
	v_mfma_f32_32x32x16_bf16 v[52:67], v[104:107], v[96:99], v[52:67]
	s_waitcnt vmcnt(16)
	v_mfma_f32_32x32x16_bf16 v[20:35], v[104:107], v[100:103], v[20:35]
	s_waitcnt lgkmcnt(0)
	v_mfma_f32_32x32x16_bf16 v[36:51], v[108:111], v[96:99], v[36:51]
	v_mfma_f32_32x32x16_bf16 v[4:19], v[108:111], v[100:103], v[4:19]
	v_bitop3_b32 v96, v186, v189, 48 bitop3:0x36
	v_lshlrev_b32_e32 v100, 4, v96
	v_add_u32_e32 v96, v187, v100
	v_add_u32_e32 v100, v188, v100
	ds_read_b128 v[96:99], v96
	ds_read_b128 v[100:103], v100
	v_bitop3_b32 v104, v186, v189, 54 bitop3:0x36
	v_lshlrev_b32_e32 v104, 4, v104
	v_add_u32_e32 v105, v187, v104
	v_add_u32_e32 v104, v188, v104
	ds_read_b128 v[140:143], v105
	ds_read_b128 v[104:107], v104
	s_waitcnt vmcnt(15) lgkmcnt(3)
	v_mfma_f32_32x32x16_bf16 v[52:67], v[96:99], v[168:171], v[52:67]
	v_bitop3_b32 v108, v186, v189, 56 bitop3:0x36
	v_lshlrev_b32_e32 v108, 4, v108
	v_add_u32_e32 v109, v187, v108
	v_add_u32_e32 v108, v188, v108
	v_bitop3_b32 v116, v186, v189, 58 bitop3:0x36
	v_lshlrev_b32_e32 v116, 4, v116
	v_add_u32_e32 v117, v187, v116
	s_waitcnt vmcnt(13)
	v_mfma_f32_32x32x16_bf16 v[20:35], v[96:99], v[198:201], v[20:35]
	v_bitop3_b32 v96, v186, v189, 50 bitop3:0x36
	v_lshlrev_b32_e32 v96, 4, v96
	v_add_u32_e32 v97, v187, v96
	v_add_u32_e32 v96, v188, v96
	ds_read_b128 v[132:135], v97
	v_add_u32_e32 v116, v188, v116
	v_bitop3_b32 v124, v186, v189, 60 bitop3:0x36
	s_waitcnt lgkmcnt(3)
	v_mfma_f32_32x32x16_bf16 v[36:51], v[100:103], v[168:171], v[36:51]
	v_bitop3_b32 v156, v186, v189, 62 bitop3:0x36
	v_lshlrev_b32_e32 v124, 4, v124
	v_lshlrev_b32_e32 v156, 4, v156
	v_add_u32_e32 v125, v187, v124
	v_add_u32_e32 v124, v188, v124
	v_add_u32_e32 v157, v187, v156
	v_lshl_add_u64 v[160:161], v[180:181], 2, s[6:7]
	v_mfma_f32_32x32x16_bf16 v[4:19], v[100:103], v[198:201], v[4:19]
	v_bitop3_b32 v100, v186, v189, 52 bitop3:0x36
	v_lshlrev_b32_e32 v100, 4, v100
	v_add_u32_e32 v101, v187, v100
	ds_read_b128 v[136:139], v101
	ds_read_b128 v[96:99], v96
	v_add_u32_e32 v100, v188, v100
	ds_read_b128 v[100:103], v100
	s_waitcnt lgkmcnt(3)
	v_mfma_f32_32x32x16_bf16 v[52:67], v[132:135], v[190:193], v[52:67]
	v_lshlrev_b32_e32 v162, 13, v186
	s_mov_b64 s[0:1], 0xb000000
	s_waitcnt lgkmcnt(1)
	v_mfma_f32_32x32x16_bf16 v[36:51], v[96:99], v[190:193], v[36:51]
	s_waitcnt vmcnt(11)
	v_mfma_f32_32x32x16_bf16 v[52:67], v[136:139], v[164:167], v[52:67]
	s_waitcnt lgkmcnt(0)
	v_mfma_f32_32x32x16_bf16 v[36:51], v[100:103], v[164:167], v[36:51]
	v_lshlrev_b32_e32 v164, 2, v180
	v_add3_u32 v162, 0, v162, v164
	s_waitcnt vmcnt(10)
	v_mfma_f32_32x32x16_bf16 v[52:67], v[140:143], v[144:147], v[52:67]
	v_mfma_f32_32x32x16_bf16 v[36:51], v[104:107], v[144:147], v[36:51]
	ds_read_b128 v[144:147], v109
	ds_read_b128 v[108:111], v108
	s_waitcnt vmcnt(7) lgkmcnt(1)
	v_mfma_f32_32x32x16_bf16 v[52:67], v[144:147], v[148:151], v[52:67]
	s_waitcnt lgkmcnt(0)
	v_mfma_f32_32x32x16_bf16 v[36:51], v[108:111], v[148:151], v[36:51]
	ds_read_b128 v[148:151], v117
	ds_read_b128 v[116:119], v116
	ds_read_b128 v[152:155], v125
	ds_read_b128 v[124:127], v124
	s_waitcnt vmcnt(6) lgkmcnt(3)
	v_mfma_f32_32x32x16_bf16 v[52:67], v[148:151], v[128:131], v[52:67]
	s_waitcnt lgkmcnt(2)
	v_mfma_f32_32x32x16_bf16 v[36:51], v[116:119], v[128:131], v[36:51]
	v_add_u32_e32 v128, v188, v156
	ds_read_b128 v[156:159], v157
	ds_read_b128 v[128:131], v128
	s_waitcnt lgkmcnt(0)
	s_barrier
	global_load_dword v163, v[160:161], off
	s_nop 0
	global_load_dword v160, v[160:161], off offset:128
	v_mfma_f32_32x32x16_bf16 v[20:35], v[132:135], v[92:95], v[20:35]
	v_mfma_f32_32x32x16_bf16 v[20:35], v[136:139], v[88:91], v[20:35]
	v_mfma_f32_32x32x16_bf16 v[20:35], v[140:143], v[84:87], v[20:35]
	v_mfma_f32_32x32x16_bf16 v[4:19], v[96:99], v[92:95], v[4:19]
	s_waitcnt vmcnt(7)
	v_mfma_f32_32x32x16_bf16 v[20:35], v[144:147], v[80:83], v[20:35]
	v_mfma_f32_32x32x16_bf16 v[4:19], v[100:103], v[88:91], v[4:19]
	s_waitcnt vmcnt(6)
	v_mfma_f32_32x32x16_bf16 v[20:35], v[148:151], v[76:79], v[20:35]
	v_mfma_f32_32x32x16_bf16 v[4:19], v[104:107], v[84:87], v[4:19]
	s_waitcnt vmcnt(5)
	v_mfma_f32_32x32x16_bf16 v[52:67], v[152:155], v[120:123], v[52:67]
	s_waitcnt vmcnt(3)
	v_mfma_f32_32x32x16_bf16 v[20:35], v[152:155], v[72:75], v[20:35]
	v_mfma_f32_32x32x16_bf16 v[4:19], v[108:111], v[80:83], v[4:19]
	v_mfma_f32_32x32x16_bf16 v[52:67], v[156:159], v[112:115], v[52:67]
	s_waitcnt vmcnt(2)
	v_mfma_f32_32x32x16_bf16 v[20:35], v[156:159], v[68:71], v[20:35]
	s_waitcnt vmcnt(1)
	s_nop 8
	v_add_f32_e32 v52, v52, v163
	v_add_f32_e32 v53, v53, v163
	v_add_f32_e32 v54, v54, v163
	v_add_f32_e32 v55, v55, v163
	v_add_f32_e32 v56, v56, v163
	v_add_f32_e32 v57, v57, v163
	v_add_f32_e32 v58, v58, v163
	v_mfma_f32_32x32x16_bf16 v[4:19], v[116:119], v[76:79], v[4:19]
	s_waitcnt vmcnt(0)
	v_add_f32_e32 v20, v20, v160
	ds_write2_b32 v162, v52, v20 offset1:32
	v_add_f32_e32 v20, v21, v160
	v_add_u32_e32 v21, 0x800, v162
	ds_write2_b32 v21, v53, v20 offset1:32
	v_add_f32_e32 v20, v22, v160
	v_add_u32_e32 v21, 0x1000, v162
	v_mfma_f32_32x32x16_bf16 v[4:19], v[124:127], v[72:75], v[4:19]
	ds_write2_b32 v21, v54, v20 offset1:32
	v_add_f32_e32 v20, v23, v160
	v_add_u32_e32 v21, 0x1800, v162
	ds_write2_b32 v21, v55, v20 offset1:32
	v_add_f32_e32 v20, v24, v160
	v_add_u32_e32 v21, 0x4000, v162
	ds_write2_b32 v21, v56, v20 offset1:32
	v_add_f32_e32 v20, v25, v160
	v_add_u32_e32 v21, 0x4800, v162
	v_mfma_f32_32x32x16_bf16 v[36:51], v[124:127], v[120:123], v[36:51]
	ds_write2_b32 v21, v57, v20 offset1:32
	v_add_f32_e32 v20, v26, v160
	v_add_u32_e32 v21, 0x5000, v162
	v_add_f32_e32 v59, v59, v163
	ds_write2_b32 v21, v58, v20 offset1:32
	v_add_f32_e32 v20, v27, v160
	v_add_u32_e32 v21, 0x5800, v162
	v_add_f32_e32 v60, v60, v163
	ds_write2_b32 v21, v59, v20 offset1:32
	v_add_f32_e32 v20, v28, v160
	v_add_u32_e32 v21, 0x8000, v162
	v_mfma_f32_32x32x16_bf16 v[4:19], v[128:131], v[68:71], v[4:19]
	v_add_f32_e32 v61, v61, v163
	ds_write2_b32 v21, v60, v20 offset1:32
	v_add_f32_e32 v20, v29, v160
	v_add_u32_e32 v21, 0x8800, v162
	v_add_f32_e32 v62, v62, v163
	ds_write2_b32 v21, v61, v20 offset1:32
	v_add_f32_e32 v20, v30, v160
	v_add_u32_e32 v21, 0x9000, v162
	v_add_f32_e32 v63, v63, v163
	ds_write2_b32 v21, v62, v20 offset1:32
	v_add_f32_e32 v20, v31, v160
	v_add_u32_e32 v21, 0x9800, v162
	v_add_f32_e32 v64, v64, v163
	ds_write2_b32 v21, v63, v20 offset1:32
	v_add_f32_e32 v20, v32, v160
	v_add_u32_e32 v21, 0xc000, v162
	v_add_f32_e32 v65, v65, v163
	ds_write2_b32 v21, v64, v20 offset1:32
	v_add_f32_e32 v20, v33, v160
	v_add_u32_e32 v21, 0xc800, v162
	v_mfma_f32_32x32x16_bf16 v[36:51], v[128:131], v[112:115], v[36:51]
	v_add_f32_e32 v66, v66, v163
	ds_write2_b32 v21, v65, v20 offset1:32
	v_add_f32_e32 v20, v34, v160
	v_add_u32_e32 v21, 0xd000, v162
	v_add_f32_e32 v67, v67, v163
	ds_write2_b32 v21, v66, v20 offset1:32
	v_add_f32_e32 v20, v35, v160
	v_add_u32_e32 v21, 0xd800, v162
	ds_write2_b32 v21, v67, v20 offset1:32
	v_add_u32_e32 v20, 0x10080, v162
	v_add_f32_e32 v4, v4, v160
	ds_write_b32 v20, v4
	v_add_f32_e32 v4, v5, v160
	v_add_u32_e32 v5, 0x10880, v162
	ds_write_b32 v5, v4
	v_add_f32_e32 v4, v6, v160
	v_add_u32_e32 v5, 0x11080, v162
	ds_write_b32 v5, v4
	v_add_f32_e32 v4, v7, v160
	v_add_u32_e32 v5, 0x11880, v162
	ds_write_b32 v5, v4
	v_add_f32_e32 v4, v8, v160
	v_add_u32_e32 v5, 0x14080, v162
	ds_write_b32 v5, v4
	v_add_f32_e32 v4, v9, v160
	v_add_u32_e32 v5, 0x14880, v162
	v_add_u32_e32 v112, 0x10000, v162
	v_add_f32_e32 v36, v36, v163
	ds_write_b32 v5, v4
	v_add_f32_e32 v4, v10, v160
	v_add_u32_e32 v5, 0x15080, v162
	ds_write_b32 v112, v36
	v_add_f32_e32 v36, v37, v163
	v_add_u32_e32 v37, 0x10800, v162
	ds_write_b32 v5, v4
	v_add_f32_e32 v4, v11, v160
	v_add_u32_e32 v5, 0x15880, v162
	ds_write_b32 v37, v36
	v_add_f32_e32 v36, v38, v163
	v_add_u32_e32 v37, 0x11000, v162
	ds_write_b32 v5, v4
	v_add_f32_e32 v4, v12, v160
	v_add_u32_e32 v5, 0x18080, v162
	ds_write_b32 v37, v36
	v_add_f32_e32 v36, v39, v163
	v_add_u32_e32 v37, 0x11800, v162
	ds_write_b32 v5, v4
	v_add_f32_e32 v4, v13, v160
	v_add_u32_e32 v5, 0x18880, v162
	ds_write_b32 v37, v36
	v_add_f32_e32 v36, v40, v163
	v_add_u32_e32 v37, 0x14000, v162
	ds_write_b32 v5, v4
	v_add_f32_e32 v4, v14, v160
	v_add_u32_e32 v5, 0x19080, v162
	ds_write_b32 v37, v36
	v_add_f32_e32 v36, v41, v163
	v_add_u32_e32 v37, 0x14800, v162
	ds_write_b32 v5, v4
	v_add_f32_e32 v4, v15, v160
	v_add_u32_e32 v5, 0x19880, v162
	ds_write_b32 v37, v36
	v_add_f32_e32 v36, v42, v163
	v_add_u32_e32 v37, 0x15000, v162
	ds_write_b32 v5, v4
	v_add_f32_e32 v4, v16, v160
	v_add_u32_e32 v5, 0x1c080, v162
	ds_write_b32 v37, v36
	v_add_f32_e32 v36, v43, v163
	v_add_u32_e32 v37, 0x15800, v162
	ds_write_b32 v5, v4
	v_add_f32_e32 v4, v17, v160
	v_add_u32_e32 v5, 0x1c880, v162
	ds_write_b32 v37, v36
	v_add_f32_e32 v36, v44, v163
	v_add_u32_e32 v37, 0x18000, v162
	ds_write_b32 v5, v4
	v_add_f32_e32 v4, v18, v160
	v_add_u32_e32 v5, 0x1d080, v162
	ds_write_b32 v37, v36
	v_add_f32_e32 v36, v45, v163
	v_add_u32_e32 v37, 0x18800, v162
	ds_write_b32 v5, v4
	v_add_f32_e32 v4, v19, v160
	v_add_u32_e32 v5, 0x1d880, v162
	ds_write_b32 v37, v36
	v_add_f32_e32 v36, v46, v163
	v_add_u32_e32 v37, 0x19000, v162
	ds_write_b32 v5, v4
	v_lshlrev_b32_e32 v4, 3, v3
	ds_write_b32 v37, v36
	v_add_f32_e32 v36, v47, v163
	v_add_u32_e32 v37, 0x19800, v162
	v_and_b32_e32 v46, 0x1f8, v4
	v_ashrrev_i32_e32 v44, 6, v3
	v_add_u32_e32 v8, 0x200, v3
	ds_write_b32 v37, v36
	v_add_f32_e32 v36, v48, v163
	v_add_u32_e32 v37, 0x1c000, v162
	v_lshlrev_b32_e32 v12, 1, v46
	v_mov_b32_e32 v13, v2
	v_ashrrev_i32_e32 v45, 31, v44
	v_ashrrev_i32_e32 v54, 6, v8
	ds_write_b32 v37, v36
	v_add_f32_e32 v36, v49, v163
	v_add_u32_e32 v37, 0x1c800, v162
	v_lshl_add_u64 v[4:5], s[66:67], 0, v[12:13]
	v_lshl_add_u64 v[52:53], s[70:71], 0, v[44:45]
	v_ashrrev_i32_e32 v55, 31, v54
	ds_write_b32 v37, v36
	v_add_f32_e32 v36, v50, v163
	v_add_u32_e32 v37, 0x1d000, v162
	v_lshl_add_u64 v[4:5], v[4:5], 0, s[0:1]
	v_lshlrev_b64 v[6:7], 10, v[52:53]
	v_lshl_add_u64 v[56:57], s[70:71], 0, v[54:55]
	ds_write_b32 v37, v36
	v_add_f32_e32 v36, v51, v163
	v_add_u32_e32 v37, 0x1d800, v162
	v_lshl_add_u64 v[6:7], v[4:5], 0, v[6:7]
	v_lshlrev_b64 v[8:9], 10, v[56:57]
	ds_write_b32 v37, v36
	s_waitcnt lgkmcnt(0)
	s_barrier
	v_lshl_add_u64 v[8:9], v[4:5], 0, v[8:9]
	global_load_dwordx4 v[20:23], v[6:7], off
	global_load_dwordx4 v[24:27], v[8:9], off
	v_add_u32_e32 v6, 0x400, v3
	v_ashrrev_i32_e32 v58, 6, v6
	v_add_u32_e32 v8, 0x600, v3
	v_ashrrev_i32_e32 v59, 31, v58
	v_ashrrev_i32_e32 v62, 6, v8
	v_lshl_add_u64 v[60:61], s[70:71], 0, v[58:59]
	v_ashrrev_i32_e32 v63, 31, v62
	v_lshlrev_b64 v[6:7], 10, v[60:61]
	v_lshl_add_u64 v[64:65], s[70:71], 0, v[62:63]
	v_lshl_add_u64 v[6:7], v[4:5], 0, v[6:7]
	v_lshlrev_b64 v[8:9], 10, v[64:65]
	v_lshl_add_u64 v[8:9], v[4:5], 0, v[8:9]
	global_load_dwordx4 v[28:31], v[6:7], off
	global_load_dwordx4 v[32:35], v[8:9], off
	v_add_u32_e32 v6, 0x800, v3
	v_ashrrev_i32_e32 v66, 6, v6
	v_add_u32_e32 v8, 0xa00, v3
	v_ashrrev_i32_e32 v67, 31, v66
	v_ashrrev_i32_e32 v70, 6, v8
	v_lshl_add_u64 v[68:69], s[70:71], 0, v[66:67]
	v_ashrrev_i32_e32 v71, 31, v70
	v_lshlrev_b64 v[6:7], 10, v[68:69]
	v_lshl_add_u64 v[72:73], s[70:71], 0, v[70:71]
	v_lshl_add_u64 v[6:7], v[4:5], 0, v[6:7]
	v_lshlrev_b64 v[8:9], 10, v[72:73]
	v_lshl_add_u64 v[8:9], v[4:5], 0, v[8:9]
	global_load_dwordx4 v[36:39], v[6:7], off
	global_load_dwordx4 v[40:43], v[8:9], off
	v_add_u32_e32 v6, 0xc00, v3
	v_add_u32_e32 v3, 0xe00, v3
	v_ashrrev_i32_e32 v74, 6, v6
	v_ashrrev_i32_e32 v16, 6, v3
	v_ashrrev_i32_e32 v75, 31, v74
	v_ashrrev_i32_e32 v17, 31, v16
	v_lshl_add_u64 v[18:19], s[70:71], 0, v[74:75]
	v_lshl_add_u64 v[14:15], s[70:71], 0, v[16:17]
	v_lshlrev_b64 v[6:7], 10, v[18:19]
	v_lshlrev_b64 v[8:9], 10, v[14:15]
	v_lshl_add_u64 v[6:7], v[4:5], 0, v[6:7]
	v_lshl_add_u64 v[4:5], v[4:5], 0, v[8:9]
	global_load_dwordx4 v[8:11], v[6:7], off
	s_nop 0
	global_load_dwordx4 v[4:7], v[4:5], off
	v_lshl_add_u32 v3, v46, 2, 0
	v_lshl_add_u32 v17, v44, 11, v3
	ds_read_b128 v[44:47], v17
	ds_read_b128 v[48:51], v17 offset:16
	s_waitcnt vmcnt(7)
	v_lshlrev_b32_e32 v55, 16, v20
	v_and_b32_e32 v20, 0xffff0000, v20
	s_mov_b32 s0, 0xc600000
	s_waitcnt lgkmcnt(1)
	v_mul_f32_e32 v17, v44, v55
	v_mul_f32_e32 v20, v45, v20
	v_cvt_pk_bf16_f32 v20, v17, v20
	v_lshlrev_b32_e32 v17, 16, v21
	v_and_b32_e32 v21, 0xffff0000, v21
	v_mul_f32_e32 v17, v46, v17
	v_mul_f32_e32 v21, v47, v21
	v_cvt_pk_bf16_f32 v21, v17, v21
	v_lshlrev_b32_e32 v17, 16, v22
	v_and_b32_e32 v22, 0xffff0000, v22
	s_waitcnt lgkmcnt(0)
	v_mul_f32_e32 v17, v48, v17
	v_mul_f32_e32 v22, v49, v22
	v_cvt_pk_bf16_f32 v22, v17, v22
	v_lshlrev_b32_e32 v17, 16, v23
	v_and_b32_e32 v23, 0xffff0000, v23
	v_mul_f32_e32 v17, v50, v17
	v_mul_f32_e32 v23, v51, v23
	v_lshlrev_b64 v[44:45], 12, v[52:53]
	v_cvt_pk_bf16_f32 v23, v17, v23
	v_lshl_add_u64 v[44:45], s[66:67], 0, v[44:45]
	v_lshl_add_u32 v17, v54, 11, v3
	v_lshl_add_u64 v[48:49], v[44:45], 0, v[12:13]
	ds_read_b128 v[44:47], v17
	v_add_co_u32_e32 v48, vcc, s0, v48
	v_lshlrev_b64 v[18:19], 12, v[18:19]
	s_nop 0
	v_addc_co_u32_e32 v49, vcc, 0, v49, vcc
	global_store_dwordx4 v[48:49], v[20:23], off offset:3072 sc0 sc1
	ds_read_b128 v[20:23], v17 offset:16
	s_waitcnt vmcnt(7)
	v_lshlrev_b32_e32 v17, 16, v24
	v_and_b32_e32 v24, 0xffff0000, v24
	s_waitcnt lgkmcnt(1)
	v_mul_f32_e32 v17, v44, v17
	v_mul_f32_e32 v24, v45, v24
	v_cvt_pk_bf16_f32 v24, v17, v24
	v_lshlrev_b32_e32 v17, 16, v25
	v_and_b32_e32 v25, 0xffff0000, v25
	v_mul_f32_e32 v17, v46, v17
	v_mul_f32_e32 v25, v47, v25
	v_cvt_pk_bf16_f32 v25, v17, v25
	v_lshlrev_b32_e32 v17, 16, v26
	s_waitcnt lgkmcnt(0)
	v_mul_f32_e32 v17, v20, v17
	v_and_b32_e32 v20, 0xffff0000, v26
	v_mul_f32_e32 v20, v21, v20
	v_cvt_pk_bf16_f32 v26, v17, v20
	v_and_b32_e32 v20, 0xffff0000, v27
	v_lshlrev_b32_e32 v17, 16, v27
	v_mul_f32_e32 v20, v23, v20
	v_mul_f32_e32 v17, v22, v17
	v_cvt_pk_bf16_f32 v27, v17, v20
	v_lshlrev_b64 v[20:21], 12, v[56:57]
	v_lshl_add_u64 v[20:21], s[66:67], 0, v[20:21]
	v_lshl_add_u32 v17, v58, 11, v3
	v_lshl_add_u64 v[44:45], v[20:21], 0, v[12:13]
	ds_read_b128 v[20:23], v17
	v_add_co_u32_e32 v44, vcc, s0, v44
	v_lshl_add_u64 v[18:19], s[66:67], 0, v[18:19]
	s_nop 0
	v_addc_co_u32_e32 v45, vcc, 0, v45, vcc
	global_store_dwordx4 v[44:45], v[24:27], off offset:3072 sc0 sc1
	ds_read_b128 v[24:27], v17 offset:16
	s_waitcnt vmcnt(7)
	v_lshlrev_b32_e32 v17, 16, v28
	s_waitcnt lgkmcnt(1)
	v_mul_f32_e32 v17, v20, v17
	v_and_b32_e32 v20, 0xffff0000, v28
	v_mul_f32_e32 v20, v21, v20
	v_cvt_pk_bf16_f32 v20, v17, v20
	v_lshlrev_b32_e32 v17, 16, v29
	v_and_b32_e32 v21, 0xffff0000, v29
	v_mul_f32_e32 v17, v22, v17
	v_mul_f32_e32 v21, v23, v21
	v_cvt_pk_bf16_f32 v21, v17, v21
	v_lshlrev_b32_e32 v17, 16, v30
	v_and_b32_e32 v22, 0xffff0000, v30
	s_waitcnt lgkmcnt(0)
	v_mul_f32_e32 v17, v24, v17
	v_mul_f32_e32 v22, v25, v22
	v_cvt_pk_bf16_f32 v22, v17, v22
	v_lshlrev_b32_e32 v17, 16, v31
	v_and_b32_e32 v23, 0xffff0000, v31
	v_mul_f32_e32 v17, v26, v17
	v_mul_f32_e32 v23, v27, v23
	v_lshlrev_b64 v[24:25], 12, v[60:61]
	v_cvt_pk_bf16_f32 v23, v17, v23
	v_lshl_add_u64 v[24:25], s[66:67], 0, v[24:25]
	v_lshl_add_u32 v17, v62, 11, v3
	v_lshl_add_u64 v[28:29], v[24:25], 0, v[12:13]
	ds_read_b128 v[24:27], v17
	v_add_co_u32_e32 v28, vcc, s0, v28
	s_movk_i32 s6, 0x4000
	s_nop 0
	v_addc_co_u32_e32 v29, vcc, 0, v29, vcc
	global_store_dwordx4 v[28:29], v[20:23], off offset:3072 sc0 sc1
	ds_read_b128 v[20:23], v17 offset:16
	s_waitcnt vmcnt(7)
	v_lshlrev_b32_e32 v17, 16, v32
	s_waitcnt lgkmcnt(1)
	v_mul_f32_e32 v17, v24, v17
	v_and_b32_e32 v24, 0xffff0000, v32
	v_mul_f32_e32 v24, v25, v24
	v_cvt_pk_bf16_f32 v24, v17, v24
	v_lshlrev_b32_e32 v17, 16, v33
	v_and_b32_e32 v25, 0xffff0000, v33
	v_mul_f32_e32 v17, v26, v17
	v_mul_f32_e32 v25, v27, v25
	v_cvt_pk_bf16_f32 v25, v17, v25
	v_lshlrev_b32_e32 v17, 16, v34
	s_waitcnt lgkmcnt(0)
	v_mul_f32_e32 v17, v20, v17
	v_and_b32_e32 v20, 0xffff0000, v34
	v_mul_f32_e32 v20, v21, v20
	v_cvt_pk_bf16_f32 v26, v17, v20
	v_and_b32_e32 v20, 0xffff0000, v35
	v_lshlrev_b32_e32 v17, 16, v35
	v_mul_f32_e32 v20, v23, v20
	v_mul_f32_e32 v17, v22, v17
	v_cvt_pk_bf16_f32 v27, v17, v20
	v_lshlrev_b64 v[20:21], 12, v[64:65]
	v_lshl_add_u64 v[20:21], s[66:67], 0, v[20:21]
	v_lshl_add_u32 v17, v66, 11, v3
	v_lshl_add_u64 v[28:29], v[20:21], 0, v[12:13]
	ds_read_b128 v[20:23], v17
	v_add_co_u32_e32 v28, vcc, s0, v28
	s_nop 1
	v_addc_co_u32_e32 v29, vcc, 0, v29, vcc
	global_store_dwordx4 v[28:29], v[24:27], off offset:3072 sc0 sc1
	ds_read_b128 v[24:27], v17 offset:16
	s_waitcnt vmcnt(7)
	v_lshlrev_b32_e32 v17, 16, v36
	s_waitcnt lgkmcnt(1)
	v_mul_f32_e32 v17, v20, v17
	v_and_b32_e32 v20, 0xffff0000, v36
	v_mul_f32_e32 v20, v21, v20
	v_cvt_pk_bf16_f32 v20, v17, v20
	v_lshlrev_b32_e32 v17, 16, v37
	v_and_b32_e32 v21, 0xffff0000, v37
	v_mul_f32_e32 v17, v22, v17
	v_mul_f32_e32 v21, v23, v21
	v_cvt_pk_bf16_f32 v21, v17, v21
	v_lshlrev_b32_e32 v17, 16, v38
	v_and_b32_e32 v22, 0xffff0000, v38
	s_waitcnt lgkmcnt(0)
	v_mul_f32_e32 v17, v24, v17
	v_mul_f32_e32 v22, v25, v22
	v_cvt_pk_bf16_f32 v22, v17, v22
	v_lshlrev_b32_e32 v17, 16, v39
	v_and_b32_e32 v23, 0xffff0000, v39
	v_mul_f32_e32 v17, v26, v17
	v_mul_f32_e32 v23, v27, v23
	v_lshlrev_b64 v[24:25], 12, v[68:69]
	v_cvt_pk_bf16_f32 v23, v17, v23
	v_lshl_add_u64 v[24:25], s[66:67], 0, v[24:25]
	v_lshl_add_u32 v17, v70, 11, v3
	v_lshl_add_u64 v[28:29], v[24:25], 0, v[12:13]
	ds_read_b128 v[24:27], v17
	v_add_co_u32_e32 v28, vcc, s0, v28
	s_nop 1
	v_addc_co_u32_e32 v29, vcc, 0, v29, vcc
	global_store_dwordx4 v[28:29], v[20:23], off offset:3072 sc0 sc1
	ds_read_b128 v[20:23], v17 offset:16
	s_waitcnt vmcnt(7)
	v_lshlrev_b32_e32 v17, 16, v40
	s_waitcnt lgkmcnt(1)
	v_mul_f32_e32 v17, v24, v17
	v_and_b32_e32 v24, 0xffff0000, v40
	v_mul_f32_e32 v24, v25, v24
	v_cvt_pk_bf16_f32 v24, v17, v24
	v_lshlrev_b32_e32 v17, 16, v41
	v_and_b32_e32 v25, 0xffff0000, v41
	v_mul_f32_e32 v17, v26, v17
	v_mul_f32_e32 v25, v27, v25
	v_cvt_pk_bf16_f32 v25, v17, v25
	v_lshlrev_b32_e32 v17, 16, v42
	s_waitcnt lgkmcnt(0)
	v_mul_f32_e32 v17, v20, v17
	v_and_b32_e32 v20, 0xffff0000, v42
	v_mul_f32_e32 v20, v21, v20
	v_cvt_pk_bf16_f32 v26, v17, v20
	v_and_b32_e32 v20, 0xffff0000, v43
	v_lshlrev_b32_e32 v17, 16, v43
	v_mul_f32_e32 v20, v23, v20
	v_mul_f32_e32 v17, v22, v17
	v_cvt_pk_bf16_f32 v27, v17, v20
	v_lshlrev_b64 v[20:21], 12, v[72:73]
	v_lshl_add_u64 v[20:21], s[66:67], 0, v[20:21]
	v_lshl_add_u32 v17, v74, 11, v3
	v_lshl_add_u64 v[28:29], v[20:21], 0, v[12:13]
	ds_read_b128 v[20:23], v17
	v_add_co_u32_e32 v28, vcc, s0, v28
	v_lshl_add_u32 v3, v16, 11, v3
	s_nop 0
	v_addc_co_u32_e32 v29, vcc, 0, v29, vcc
	global_store_dwordx4 v[28:29], v[24:27], off offset:3072 sc0 sc1
	ds_read_b128 v[24:27], v17 offset:16
	s_waitcnt vmcnt(7)
	v_lshlrev_b32_e32 v17, 16, v8
	v_and_b32_e32 v8, 0xffff0000, v8
	s_waitcnt lgkmcnt(1)
	v_mul_f32_e32 v17, v20, v17
	v_mul_f32_e32 v8, v21, v8
	v_cvt_pk_bf16_f32 v8, v17, v8
	v_lshlrev_b32_e32 v17, 16, v9
	v_and_b32_e32 v9, 0xffff0000, v9
	v_mul_f32_e32 v17, v22, v17
	v_mul_f32_e32 v9, v23, v9
	v_cvt_pk_bf16_f32 v9, v17, v9
	v_lshlrev_b32_e32 v17, 16, v10
	v_and_b32_e32 v10, 0xffff0000, v10
	s_waitcnt lgkmcnt(0)
	v_mul_f32_e32 v17, v24, v17
	v_mul_f32_e32 v10, v25, v10
	v_cvt_pk_bf16_f32 v10, v17, v10
	v_lshlrev_b32_e32 v17, 16, v11
	v_and_b32_e32 v11, 0xffff0000, v11
	v_mul_f32_e32 v17, v26, v17
	v_mul_f32_e32 v11, v27, v11
	v_cvt_pk_bf16_f32 v11, v17, v11
	v_lshl_add_u64 v[20:21], v[18:19], 0, v[12:13]
	ds_read_b128 v[16:19], v3
	v_add_co_u32_e32 v20, vcc, s0, v20
	s_nop 1
	v_addc_co_u32_e32 v21, vcc, 0, v21, vcc
	global_store_dwordx4 v[20:21], v[8:11], off offset:3072 sc0 sc1
	ds_read_b128 v[8:11], v3 offset:16
	s_waitcnt vmcnt(7)
	v_lshlrev_b32_e32 v3, 16, v4
	v_and_b32_e32 v4, 0xffff0000, v4
	s_waitcnt lgkmcnt(1)
	v_mul_f32_e32 v3, v16, v3
	v_mul_f32_e32 v4, v17, v4
	v_cvt_pk_bf16_f32 v4, v3, v4
	v_lshlrev_b32_e32 v3, 16, v5
	v_and_b32_e32 v5, 0xffff0000, v5
	v_mul_f32_e32 v3, v18, v3
	v_mul_f32_e32 v5, v19, v5
	v_cvt_pk_bf16_f32 v5, v3, v5
	v_lshlrev_b32_e32 v3, 16, v6
	v_and_b32_e32 v6, 0xffff0000, v6
	s_waitcnt lgkmcnt(0)
	v_mul_f32_e32 v3, v8, v3
	v_mul_f32_e32 v6, v9, v6
	v_lshlrev_b64 v[8:9], 12, v[14:15]
	v_lshl_add_u64 v[8:9], s[66:67], 0, v[8:9]
	v_lshl_add_u64 v[8:9], v[8:9], 0, v[12:13]
	v_cvt_pk_bf16_f32 v6, v3, v6
	v_lshlrev_b32_e32 v3, 16, v7
	v_and_b32_e32 v7, 0xffff0000, v7
	v_add_co_u32_e32 v8, vcc, 0xc600000, v8
	v_mul_f32_e32 v7, v11, v7
	s_nop 0
	v_addc_co_u32_e32 v9, vcc, 0, v9, vcc
	v_mul_f32_e32 v3, v10, v3
	v_cvt_pk_bf16_f32 v7, v3, v7
	global_store_dwordx4 v[8:9], v[4:7], off offset:3072 sc0 sc1
	s_barrier
	s_branch .LBB0_438

.LBB0_596:
	v_add_u32_e32 v16, 0, v9
	v_add_u32_e32 v18, 0, v3
	ds_read2st64_b32 v[10:11], v16 offset1:8
	v_add_u32_e32 v19, 0x10000, v18
	v_add_u32_e32 v20, 0x10020, v18
	v_add_u32_e32 v22, 0x10040, v18
	v_add_u32_e32 v24, 0x10060, v18
	v_add_u32_e32 v26, 0x10080, v18
	v_add_u32_e32 v28, 0x100a0, v18
	v_add_u32_e32 v30, 0x100c0, v18
	v_add_u32_e32 v32, 0x100e0, v18
	ds_read2st64_b32 v[12:13], v16 offset0:16 offset1:24
	ds_read2st64_b32 v[14:15], v16 offset0:32 offset1:40
	ds_read2st64_b32 v[16:17], v16 offset0:48 offset1:56
	ds_read_b64 v[18:19], v19
	ds_read_b64 v[20:21], v20
	ds_read_b64 v[22:23], v22
	ds_read_b64 v[24:25], v24
	ds_read_b64 v[26:27], v26
	ds_read_b64 v[28:29], v28
	ds_read_b64 v[30:31], v30
	ds_read_b64 v[32:33], v32
	s_waitcnt lgkmcnt(7)
	v_sub_f32_e32 v18, v18, v5
	v_mov_b32_e32 v34, v19
	s_waitcnt lgkmcnt(6)
	v_sub_f32_e32 v19, v20, v5
	v_exp_f32_e32 v18, v18
	v_mov_b32_e32 v35, v10
	v_mov_b32_e32 v10, v21
	s_waitcnt lgkmcnt(5)
	v_sub_f32_e32 v21, v22, v5
	v_exp_f32_e32 v20, v19
	v_mov_b32_e32 v36, v23
	s_waitcnt lgkmcnt(4)
	v_sub_f32_e32 v23, v24, v5
	v_exp_f32_e32 v22, v21
	v_mov_b32_e32 v37, v12
	v_mov_b32_e32 v12, v25
	s_waitcnt lgkmcnt(3)
	v_sub_f32_e32 v25, v26, v5
	v_exp_f32_e32 v24, v23
	v_mov_b32_e32 v38, v27
	s_waitcnt lgkmcnt(2)
	v_sub_f32_e32 v27, v28, v5
	v_exp_f32_e32 v26, v25
	v_pk_fma_f32 v[6:7], v[18:19], v[34:35], v[6:7] op_sel_hi:[0,1,1]
	v_mov_b32_e32 v39, v14
	v_mov_b32_e32 v14, v29
	s_waitcnt lgkmcnt(1)
	v_sub_f32_e32 v29, v30, v5
	v_exp_f32_e32 v28, v27
	v_pk_fma_f32 v[6:7], v[20:21], v[10:11], v[6:7] op_sel_hi:[0,1,1]
	v_mov_b32_e32 v40, v31
	s_waitcnt lgkmcnt(0)
	v_sub_f32_e32 v31, v32, v5
	v_exp_f32_e32 v30, v29
	v_pk_fma_f32 v[6:7], v[22:23], v[36:37], v[6:7] op_sel_hi:[0,1,1]
	v_exp_f32_e32 v32, v31
	v_pk_fma_f32 v[6:7], v[24:25], v[12:13], v[6:7] op_sel_hi:[0,1,1]
	v_pk_fma_f32 v[6:7], v[26:27], v[38:39], v[6:7] op_sel_hi:[0,1,1]
	v_mov_b32_e32 v41, v16
	v_pk_fma_f32 v[6:7], v[28:29], v[14:15], v[6:7] op_sel_hi:[0,1,1]
	s_add_i32 s0, s0, -8
	v_mov_b32_e32 v16, v33
	v_pk_fma_f32 v[6:7], v[30:31], v[40:41], v[6:7] op_sel_hi:[0,1,1]
	v_add_u32_e32 v9, 0x4000, v9
	v_add_u32_e32 v3, 0x100, v3
	s_cmp_lg_u32 s0, 0
	v_pk_fma_f32 v[6:7], v[32:33], v[16:17], v[6:7] op_sel_hi:[0,1,1]
	s_cbranch_scc1 .LBB0_596
	v_div_scale_f32 v3, s[0:1], v6, v6, v7
	v_rcp_f32_e32 v9, v3
	s_lshl_b32 s2, s54, 2
	s_add_i32 s20, s2, 0x2000
	v_ashrrev_i32_e32 v5, 31, v4
	v_fma_f32 v10, -v3, v9, 1.0
	v_fmac_f32_e32 v9, v10, v9
	v_div_scale_f32 v10, vcc, v7, v6, v7
	v_mul_f32_e32 v11, v10, v9
	v_fma_f32 v12, -v3, v11, v10
	v_fmac_f32_e32 v11, v12, v9
	v_fma_f32 v3, -v3, v11, v10
	v_lshl_add_u64 v[4:5], v[4:5], 0, s[20:21]
	v_div_fmas_f32 v3, v3, v9, v11
	v_mov_b64_e32 v[10:11], s[68:69]
	v_mad_i64_i32 v[10:11], s[0:1], v4, s19, v[10:11]
	v_lshl_add_u64 v[10:11], v[10:11], 0, s[66:67]
	v_lshlrev_b32_e32 v8, 1, v8
	v_mov_b32_e32 v9, v2
	v_lshl_add_u64 v[10:11], v[10:11], 0, v[8:9]
	v_add_co_u32_e32 v10, vcc, s50, v10
	v_lshlrev_b64 v[4:5], 12, v[4:5]
	s_nop 0
	v_addc_co_u32_e32 v11, vcc, 0, v11, vcc
	global_load_ushort v10, v[10:11], off offset:1024
	v_lshl_add_u64 v[4:5], s[6:7], 0, v[4:5]
	v_lshl_add_u64 v[4:5], v[4:5], 0, s[66:67]
	v_div_fixup_f32 v3, v3, v6, v7
	v_lshl_add_u64 v[4:5], v[4:5], 0, v[8:9]
	s_movk_i32 s0, 0x7fff
	v_add_co_u32_e32 v4, vcc, 0xc600000, v4
	s_movk_i32 s6, 0x4000
	s_nop 0
	v_addc_co_u32_e32 v5, vcc, 0, v5, vcc
	s_waitcnt vmcnt(0)
	v_lshlrev_b32_e32 v6, 16, v10
	v_mul_f32_e32 v3, v3, v6
	v_bfe_u32 v6, v3, 16, 1
	v_add3_u32 v3, v3, v6, s0
	global_store_short_d16_hi v[4:5], v3, off sc0 sc1
	s_barrier

.LBB0_599:
	s_load_dwordx16 s[0:15], s[52:53], 0x0
	v_lshlrev_b32_e32 v2, 4, v0
	v_mov_b32_e32 v3, 0
	v_readlane_b32 s48, v248, 40
	s_mov_b64 s[20:21], 0xa000
	s_waitcnt lgkmcnt(0)
	v_lshl_add_u64 v[4:5], s[6:7], 0, v[2:3]
	s_load_dwordx16 s[0:15], s[52:53], 0x40
	s_waitcnt lgkmcnt(0)
	s_mov_b64 s[0:1], 0xa31c000
	s_add_i32 s5, 0, 0x23200
	s_movk_i32 s4, 0x201
	s_mov_b32 s8, 0
	v_lshl_add_u64 v[6:7], s[14:15], 0, v[2:3]
	v_lshl_add_u64 v[6:7], v[6:7], 0, s[0:1]
	v_mov_b32_e32 v1, s5
	s_mov_b64 s[0:1], 0xc000
	s_mov_b64 s[2:3], 0x2000
	s_mov_b64 s[6:7], 0x4000
	s_mov_b64 s[12:13], 0x6000
	s_mov_b64 s[14:15], 0x8000
	s_mov_b64 s[24:25], 0xe000
	s_mov_b64 s[26:27], 0x10000
	v_mov_b32_e32 v2, 0x1800000
	v_readlane_b32 s49, v248, 41
	v_readlane_b32 s50, v248, 42
	v_readlane_b32 s33, v248, 46
	v_readlane_b32 s51, v248, 43
	s_branch .LBB0_601

.LBB0_601:
	s_barrier
	s_and_saveexec_b64 s[10:11], s[48:49]
	s_cbranch_execz .LBB0_607
	s_load_dwordx4 s[16:19], s[52:53], 0x80
	s_waitcnt lgkmcnt(0)
	global_load_dword v8, v3, s[16:17] offset:1536 sc1
	s_waitcnt vmcnt(0)
	v_cmp_lt_u32_e32 vcc, s4, v8
	v_mov_b32_e32 v8, 0x600
	s_cbranch_vccnz .LBB0_606
	s_mov_b64 s[30:31], exec
	v_mbcnt_lo_u32_b32 v8, s30, 0
	v_mbcnt_hi_u32_b32 v8, s31, v8
	v_cmp_eq_u32_e32 vcc, 0, v8
	s_and_saveexec_b64 s[28:29], vcc
	s_cbranch_execz .LBB0_605
	s_load_dwordx4 s[16:19], s[52:53], 0x80
	s_bcnt1_i32_b64 s9, s[30:31]
	v_mov_b32_e32 v9, s9
	s_waitcnt lgkmcnt(0)
	global_atomic_add v9, v3, v9, s[16:17] offset:768 sc0

.LBB0_610:
	s_waitcnt lgkmcnt(0)
	s_cmp_gt_i32 s31, 3
	s_cselect_b64 s[6:7], -1, 0
	s_and_b64 s[0:1], s[0:1], s[6:7]
	s_andn2_b64 vcc, exec, s[0:1]
	s_cbranch_vccnz .LBB0_664
	buffer_inv sc1
	s_waitcnt vmcnt(0)
	s_barrier
.LBB0_664:
	s_cmp_lg_u32 s101, 0
	s_cbranch_scc1 .Lp3_go
	s_mov_b32 s101, 1
.Lp3_go:
	s_load_dwordx4 s[8:11], s[52:53], 0x80
	s_waitcnt lgkmcnt(0)
	s_cmp_lt_i32 s10, 4
	s_cselect_b64 s[0:1], -1, 0
	s_and_b64 s[0:1], s[0:1], s[6:7]
	s_andn2_b64 vcc, exec, s[0:1]
	s_cbranch_vccnz .LBB0_735
	s_add_u32 s12, s8, 0xc600000
	s_addc_u32 s13, s9, 0
	s_add_u32 s14, s8, 0x2000000
	s_addc_u32 s15, s9, 0
	s_add_u32 s4, s8, 0xe800000
	s_addc_u32 s5, s9, 0
	s_ashr_i32 s0, s50, 1
	s_andn2_b32 s0, s0, 31
	v_and_b32_e32 v1, 15, v0
	s_addk_i32 s0, 0x2000
	v_or_b32_e32 v2, s0, v1
	v_ashrrev_i32_e32 v3, 31, v2
	v_lshlrev_b64 v[2:3], 12, v[2:3]
	v_bfe_u32 v136, v0, 4, 2
	v_lshl_add_u64 v[2:3], s[12:13], 0, v[2:3]
	v_lshlrev_b32_e32 v134, 9, v195
	v_mov_b32_e32 v135, 0
	s_lshl_b32 s1, s50, 5
	v_lshl_add_u64 v[2:3], v[2:3], 0, v[134:135]
	v_lshlrev_b32_e32 v4, 4, v136
	v_mov_b32_e32 v5, v135
	s_and_b32 s1, s1, 0x7e0
	v_lshl_add_u64 v[66:67], v[2:3], 0, v[4:5]
	v_or_b32_e32 v2, s1, v1
	v_lshlrev_b32_e32 v2, 12, v2
	v_mov_b32_e32 v3, v135
	v_lshl_add_u64 v[2:3], s[14:15], 0, v[2:3]
	s_mov_b32 s2, 0x10000
	v_lshl_add_u64 v[2:3], v[2:3], 0, v[134:135]
	v_add_co_u32_e32 v118, vcc, s2, v66
	v_lshl_add_u64 v[68:69], v[2:3], 0, v[4:5]
	s_nop 0
	v_addc_co_u32_e32 v119, vcc, 0, v67, vcc
	v_add_co_u32_e32 v126, vcc, s2, v68
	global_load_dwordx4 v[2:5], v[66:67], off
	global_load_dwordx4 v[6:9], v[66:67], off offset:64
	global_load_dwordx4 v[10:13], v[68:69], off
	global_load_dwordx4 v[14:17], v[68:69], off offset:64
	global_load_dwordx4 v[18:21], v[66:67], off offset:128
	global_load_dwordx4 v[22:25], v[66:67], off offset:192
	global_load_dwordx4 v[26:29], v[68:69], off offset:128
	global_load_dwordx4 v[30:33], v[68:69], off offset:192
	global_load_dwordx4 v[34:37], v[66:67], off offset:256
	global_load_dwordx4 v[38:41], v[66:67], off offset:320
	global_load_dwordx4 v[42:45], v[68:69], off offset:256
	global_load_dwordx4 v[46:49], v[68:69], off offset:320
	global_load_dwordx4 v[50:53], v[66:67], off offset:384
	global_load_dwordx4 v[54:57], v[66:67], off offset:448
	global_load_dwordx4 v[58:61], v[68:69], off offset:384
	global_load_dwordx4 v[62:65], v[68:69], off offset:448
	v_addc_co_u32_e32 v127, vcc, 0, v69, vcc
	global_load_dwordx4 v[66:69], v[118:119], off
	global_load_dwordx4 v[70:73], v[118:119], off offset:64
	global_load_dwordx4 v[74:77], v[126:127], off
	global_load_dwordx4 v[78:81], v[126:127], off offset:64
	global_load_dwordx4 v[82:85], v[118:119], off offset:128
	global_load_dwordx4 v[86:89], v[118:119], off offset:192
	global_load_dwordx4 v[90:93], v[126:127], off offset:128
	global_load_dwordx4 v[94:97], v[126:127], off offset:192
	global_load_dwordx4 v[98:101], v[118:119], off offset:256
	global_load_dwordx4 v[102:105], v[118:119], off offset:320
	global_load_dwordx4 v[106:109], v[126:127], off offset:256
	global_load_dwordx4 v[110:113], v[126:127], off offset:320
	global_load_dwordx4 v[114:117], v[118:119], off offset:384
	s_nop 0
	global_load_dwordx4 v[118:121], v[118:119], off offset:448
	s_nop 0
	global_load_dwordx4 v[122:125], v[126:127], off offset:384
	s_nop 0
	global_load_dwordx4 v[126:129], v[126:127], off offset:448
	s_load_dword s16, s[52:53], 0x90
	s_waitcnt vmcnt(29)
	v_mfma_f32_16x16x32_bf16 v[130:133], v[2:5], v[10:13], 0
	s_movk_i32 s2, 0x1080
	s_lshl_b32 s1, s1, 2
	s_waitcnt vmcnt(13)
	v_mfma_f32_16x16x32_bf16 v[2:5], v[2:5], v[74:77], 0
	v_mfma_f32_16x16x32_bf16 v[130:133], v[6:9], v[14:17], v[130:133]
	s_waitcnt vmcnt(12)
	v_mfma_f32_16x16x32_bf16 v[2:5], v[6:9], v[78:81], v[2:5]
	v_mfma_f32_16x16x32_bf16 v[6:9], v[66:69], v[10:13], 0
	v_mfma_f32_16x16x32_bf16 v[10:13], v[66:69], v[74:77], 0
	v_mfma_f32_16x16x32_bf16 v[130:133], v[18:21], v[26:29], v[130:133]
	s_waitcnt vmcnt(9)
	v_mfma_f32_16x16x32_bf16 v[2:5], v[18:21], v[90:93], v[2:5]
	v_mfma_f32_16x16x32_bf16 v[6:9], v[70:73], v[14:17], v[6:9]
	v_mul_u32_u24_e32 v16, 0x210, v136
	v_mfma_f32_16x16x32_bf16 v[10:13], v[70:73], v[78:81], v[10:13]
	v_mfma_f32_16x16x32_bf16 v[130:133], v[22:25], v[30:33], v[130:133]
	s_waitcnt vmcnt(8)
	v_mfma_f32_16x16x32_bf16 v[2:5], v[22:25], v[94:97], v[2:5]
	v_mfma_f32_16x16x32_bf16 v[6:9], v[82:85], v[26:29], v[6:9]
	v_mfma_f32_16x16x32_bf16 v[10:13], v[82:85], v[90:93], v[10:13]
	v_mfma_f32_16x16x32_bf16 v[130:133], v[34:37], v[42:45], v[130:133]
	s_waitcnt vmcnt(5)
	v_mfma_f32_16x16x32_bf16 v[2:5], v[34:37], v[106:109], v[2:5]
	v_mfma_f32_16x16x32_bf16 v[6:9], v[86:89], v[30:33], v[6:9]
	v_mfma_f32_16x16x32_bf16 v[10:13], v[86:89], v[94:97], v[10:13]
	v_mfma_f32_16x16x32_bf16 v[130:133], v[38:41], v[46:49], v[130:133]
	s_waitcnt vmcnt(4)
	v_mfma_f32_16x16x32_bf16 v[2:5], v[38:41], v[110:113], v[2:5]
	v_mfma_f32_16x16x32_bf16 v[6:9], v[98:101], v[42:45], v[6:9]
	v_mfma_f32_16x16x32_bf16 v[12:15], v[98:101], v[106:109], v[10:13]
	v_mfma_f32_16x16x32_bf16 v[130:133], v[50:53], v[58:61], v[130:133]
	s_nop 1
	v_mad_u32_u24 v11, v195, s2, 0
	v_lshlrev_b32_e32 v10, 2, v1
	v_add3_u32 v11, v11, v10, v16
	s_waitcnt vmcnt(1)
	v_mfma_f32_16x16x32_bf16 v[2:5], v[50:53], v[122:125], v[2:5]
	s_add_u32 s2, s4, s1
	s_movk_i32 s1, 0x84
	s_addc_u32 s3, s5, 0
	v_mfma_f32_16x16x32_bf16 v[6:9], v[102:105], v[46:49], v[6:9]
	v_mfma_f32_16x16x32_bf16 v[12:15], v[102:105], v[110:113], v[12:15]
	v_mfma_f32_16x16x32_bf16 v[130:133], v[54:57], v[62:65], v[130:133]
	s_waitcnt vmcnt(0)
	v_mfma_f32_16x16x32_bf16 v[2:5], v[54:57], v[126:129], v[2:5]
	s_nop 7
	ds_write2_b32 v11, v130, v2 offset1:16
	ds_write2_b32 v11, v131, v3 offset0:33 offset1:49
	v_mfma_f32_16x16x32_bf16 v[6:9], v[114:117], v[58:61], v[6:9]
	ds_write2_b32 v11, v132, v4 offset0:66 offset1:82
	ds_write2_b32 v11, v133, v5 offset0:99 offset1:115
	v_add_u32_e32 v11, 0x800, v11
	v_mfma_f32_16x16x32_bf16 v[12:15], v[114:117], v[122:125], v[12:15]
	v_mfma_f32_16x16x32_bf16 v[6:9], v[118:121], v[62:65], v[6:9]
	v_mfma_f32_16x16x32_bf16 v[2:5], v[118:121], v[126:129], v[12:15]
	s_nop 7
	ds_write2_b32 v11, v6, v2 offset0:16 offset1:32
	ds_write2_b32 v11, v7, v3 offset0:49 offset1:65
	ds_write2_b32 v11, v8, v4 offset0:82 offset1:98
	ds_write2_b32 v11, v9, v5 offset0:115 offset1:131
	v_and_b32_e32 v2, 31, v0
	v_lshlrev_b32_e32 v134, 2, v2
	v_add_u32_e32 v6, 0, v134
	v_lshrrev_b32_e32 v4, 5, v0
	v_mad_u32_u24 v5, v4, s1, v6
	s_waitcnt lgkmcnt(0)
	s_barrier
	ds_read_b32 v7, v5
	ds_read_b32 v8, v5 offset:4224
	ds_read_b32 v9, v5 offset:8448
	ds_read_b32 v11, v5 offset:12672
	ds_read_b32 v12, v5 offset:16896
	ds_read_b32 v13, v5 offset:21120
	ds_read_b32 v14, v5 offset:25344
	ds_read_b32 v5, v5 offset:29568
	s_waitcnt lgkmcnt(7)
	v_add_f32_e32 v7, 0, v7
	s_waitcnt lgkmcnt(6)
	v_add_f32_e32 v7, v7, v8
	s_waitcnt lgkmcnt(5)
	v_add_f32_e32 v7, v7, v9
	s_waitcnt lgkmcnt(4)
	v_add_f32_e32 v7, v7, v11
	s_waitcnt lgkmcnt(3)
	v_add_f32_e32 v7, v7, v12
	s_waitcnt lgkmcnt(2)
	v_add_f32_e32 v7, v7, v13
	s_waitcnt lgkmcnt(1)
	v_add_f32_e32 v7, v7, v14
	v_or_b32_e32 v4, s0, v4
	s_waitcnt lgkmcnt(0)
	v_add_f32_e32 v7, v7, v5
	v_ashrrev_i32_e32 v5, 31, v4
	v_lshl_add_u64 v[2:3], s[2:3], 0, v[134:135]
	v_lshlrev_b64 v[4:5], 13, v[4:5]
	v_lshl_add_u64 v[4:5], v[2:3], 0, v[4:5]
	global_store_dword v[4:5], v7, off sc0 sc1
	v_or_b32_e32 v4, 0x200, v0
	v_lshrrev_b32_e32 v4, 5, v4
	v_mad_u32_u24 v5, v4, s1, v6
	ds_read_b32 v6, v5
	ds_read_b32 v7, v5 offset:4224
	ds_read_b32 v8, v5 offset:8448
	ds_read_b32 v9, v5 offset:12672
	ds_read_b32 v11, v5 offset:16896
	ds_read_b32 v12, v5 offset:21120
	ds_read_b32 v13, v5 offset:25344
	ds_read_b32 v5, v5 offset:29568
	s_waitcnt lgkmcnt(7)
	v_add_f32_e32 v6, 0, v6
	s_waitcnt lgkmcnt(6)
	v_add_f32_e32 v6, v6, v7
	s_waitcnt lgkmcnt(5)
	v_add_f32_e32 v6, v6, v8
	s_waitcnt lgkmcnt(4)
	v_add_f32_e32 v6, v6, v9
	s_waitcnt lgkmcnt(3)
	v_add_f32_e32 v6, v6, v11
	s_waitcnt lgkmcnt(2)
	v_add_f32_e32 v6, v6, v12
	s_waitcnt lgkmcnt(1)
	v_add_f32_e32 v6, v6, v13
	v_or_b32_e32 v4, s0, v4
	s_waitcnt lgkmcnt(0)
	v_add_f32_e32 v6, v6, v5
	v_ashrrev_i32_e32 v5, 31, v4
	v_lshlrev_b64 v[4:5], 13, v[4:5]
	v_lshl_add_u64 v[2:3], v[2:3], 0, v[4:5]
	global_store_dword v[2:3], v6, off sc0 sc1
	s_waitcnt vmcnt(0)
	s_barrier
	s_and_saveexec_b64 s[0:1], s[48:49]
	s_cbranch_execz .LBB0_668
	s_mov_b64 s[2:3], exec
	v_mbcnt_lo_u32_b32 v2, s2, 0
	s_nop 0
	s_waitcnt vmcnt(0)
	s_waitcnt vmcnt(0)
	v_mbcnt_hi_u32_b32 v2, s3, v2
	v_cmp_eq_u32_e32 vcc, 0, v2
	s_and_b64 s[6:7], exec, vcc
	s_mov_b64 exec, s[6:7]
	s_cbranch_execz .LBB0_668
	s_bcnt1_i32_b64 s2, s[2:3]
	v_readlane_b32 s8, v248, 32
	v_mov_b32_e32 v2, 0xa000
	v_mov_b32_e32 v3, s2
	v_readlane_b32 s9, v248, 33
	v_readlane_b32 s10, v248, 34
	v_readlane_b32 s11, v248, 35
	s_nop 2
	global_atomic_add v2, v3, s[8:9]
.LBB0_668:
	s_or_b64 exec, exec, s[0:1]
	s_cmp_eq_u32 s101, 3
	s_cbranch_scc1 .LBB0_721
	s_cmpk_gt_i32 s50, 0xff
	v_readfirstlane_b32 s18, v0
	s_barrier
	s_cbranch_scc1 .LBB0_721
	s_ashr_i32 s22, s50, 31
	s_lshr_b32 s0, s22, 29
	s_add_i32 s6, s50, s0
	s_and_b32 s0, s6, -8
	s_sub_i32 s3, s50, s0
	s_cmp_gt_i32 s3, -1
	s_cbranch_scc0 .LBB0_671
	s_lshl_b32 s2, s3, 5
	s_ashr_i32 s0, s6, 3
	s_cbranch_execz .LBB0_672
	s_branch .LBB0_673

.LBB0_721:
	s_cmp_lg_u32 s101, 1
	s_cbranch_scc1 .Lp3_final
	v_readlane_b32 s0, v248, 32
	v_readlane_b32 s1, v248, 33
	v_mov_b32_e32 v1, 0
	s_mov_b32 s3, 0
	s_nop 4
.Lp3_wait:
	global_load_dword v2, v1, s[0:1] offset:512 sc1
	s_waitcnt vmcnt(0)
	v_readfirstlane_b32 s2, v2
	s_cmpk_gt_u32 s2, 0x381
	s_cbranch_scc1 .Lp3_waited
	s_add_u32 s3, s3, 1
	s_cmp_gt_u32 s3, 0x200000
	s_cbranch_scc1 .Lp3_waited
	s_sleep 8
	s_branch .Lp3_wait
.Lp3_waited:
	buffer_inv sc1
	s_waitcnt vmcnt(0) lgkmcnt(0)
	s_barrier
	v_readlane_b32 s50, v248, 42
	v_readlane_b32 s48, v248, 40
	v_readlane_b32 s49, v248, 41
	v_readlane_b32 s51, v248, 43
	v_readlane_b32 s52, v251, 0
	v_readlane_b32 s53, v251, 1
	s_mov_b64 s[6:7], -1
	v_lshrrev_b32_e32 v195, 6, v0
	s_mov_b32 s101, 3
	s_nop 4
	s_branch .LBB0_664
.Lp3_final:
	s_lshl_b32 s16, s16, 1
	s_cmpk_lt_i32 s50, 0x80
	s_cselect_b64 s[0:1], -1, 0
	v_cmp_gt_u32_e32 vcc, 64, v0
	s_and_b64 s[0:1], s[0:1], vcc
	s_and_saveexec_b64 s[2:3], s[0:1]
	s_cbranch_execz .LBB0_727
	v_readlane_b32 s8, v248, 32
	v_readlane_b32 s9, v248, 33
	s_mov_b64 s[0:1], s[8:9]
	s_add_u32 s0, s0, 0xa000
	s_addc_u32 s1, s1, 0
	s_mov_b32 s8, 0x100001
	v_mov_b32_e32 v1, 0
	v_readlane_b32 s10, v248, 34
	v_readlane_b32 s11, v248, 35
	s_branch .LBB0_724

	.amdhsa_kernel _Z8mega_fwd6Params
		.amdhsa_group_segment_fixed_size 0
		.amdhsa_private_segment_fixed_size 0
		.amdhsa_kernarg_size 400
		.amdhsa_user_sgpr_count 2
		.amdhsa_user_sgpr_dispatch_ptr 0
		.amdhsa_user_sgpr_queue_ptr 0
		.amdhsa_user_sgpr_kernarg_segment_ptr 1
		.amdhsa_user_sgpr_dispatch_id 0
		.amdhsa_user_sgpr_kernarg_preload_length 0
		.amdhsa_user_sgpr_kernarg_preload_offset 0
		.amdhsa_user_sgpr_private_segment_size 0
		.amdhsa_uses_dynamic_stack 0
		.amdhsa_enable_private_segment 0
		.amdhsa_system_sgpr_workgroup_id_x 1
		.amdhsa_system_sgpr_workgroup_id_y 0
		.amdhsa_system_sgpr_workgroup_id_z 0
		.amdhsa_system_sgpr_workgroup_info 0
		.amdhsa_system_vgpr_workitem_id 0
		.amdhsa_next_free_vgpr 252
		.amdhsa_next_free_sgpr 102
		.amdhsa_accum_offset 252
		.amdhsa_reserve_vcc 1
		.amdhsa_float_round_mode_32 0
		.amdhsa_float_round_mode_16_64 0
		.amdhsa_float_denorm_mode_32 3
		.amdhsa_float_denorm_mode_16_64 3
		.amdhsa_dx10_clamp 1
		.amdhsa_ieee_mode 1
		.amdhsa_fp16_overflow 0
		.amdhsa_tg_split 0
		.amdhsa_exception_fp_ieee_invalid_op 0
		.amdhsa_exception_fp_denorm_src 0
		.amdhsa_exception_fp_ieee_div_zero 0
		.amdhsa_exception_fp_ieee_overflow 0
		.amdhsa_exception_fp_ieee_underflow 0
		.amdhsa_exception_fp_ieee_inexact 0
		.amdhsa_exception_int_div_zero 0
	.end_amdhsa_kernel

amdhsa.kernels:
  - .agpr_count:     0
    .args:
      - .offset:         0
        .size:           144
        .value_kind:     by_value
      - .offset:         144
        .size:           4
        .value_kind:     hidden_block_count_x
      - .offset:         148
        .size:           4
        .value_kind:     hidden_block_count_y
      - .offset:         152
        .size:           4
        .value_kind:     hidden_block_count_z
      - .offset:         156
        .size:           2
        .value_kind:     hidden_group_size_x
      - .offset:         158
        .size:           2
        .value_kind:     hidden_group_size_y
      - .offset:         160
        .size:           2
        .value_kind:     hidden_group_size_z
      - .offset:         162
        .size:           2
        .value_kind:     hidden_remainder_x
      - .offset:         164
        .size:           2
        .value_kind:     hidden_remainder_y
      - .offset:         166
        .size:           2
        .value_kind:     hidden_remainder_z
      - .offset:         184
        .size:           8
        .value_kind:     hidden_global_offset_x
      - .offset:         192
        .size:           8
        .value_kind:     hidden_global_offset_y
      - .offset:         200
        .size:           8
        .value_kind:     hidden_global_offset_z
      - .offset:         208
        .size:           2
        .value_kind:     hidden_grid_dims
      - .offset:         264
        .size:           4
        .value_kind:     hidden_dynamic_lds_size
    .group_segment_fixed_size: 0
    .kernarg_segment_align: 8
    .kernarg_segment_size: 400
    .language:       OpenCL C
    .language_version:
      - 2
      - 0
    .max_flat_workgroup_size: 512
    .name:           _Z8mega_fwd6Params
    .private_segment_fixed_size: 0
    .sgpr_count:     108
    .sgpr_spill_count: 57
    .symbol:         _Z8mega_fwd6Params.kd
    .uniform_work_group_size: 1
    .uses_dynamic_stack: false
    .vgpr_count:     252
    .vgpr_spill_count: 0
    .wavefront_size: 64
